# big-GEMM K loops: first half K-tile peeled with C=0, 127 accumulator-zeroing moves per unit removed (proj, mix-out, FFN-in, FFN-out)
# speedup vs baseline: 1.0200x; 1.0095x over previous
; #define PG8_STAGE(bufoff, gbase, voff) do { _Pragma("unroll") for (int _i = 0; _i < 2; ++_i) \
;         __builtin_amdgcn_global_load_lds((const unsigned*)((const char*)(gbase) + (voff)[_i]), (LAS unsigned*)(lds + (bufoff) + ldsw + _i * 8192), 16, 0, 0); } while (0)
; #define PG8_WAIT_V(n) asm volatile("s_waitcnt vmcnt(" #n ")" ::: "memory")
; #define PG8_BAR __builtin_amdgcn_s_barrier()
; template <class Epi, class Sched>
; DI void gemm_phase(LAS unsigned char* lds, const Gemm g, const Sched& S, const Epi& E) {
;     ...
;     f32x4 acc[2][2][4][2];
; #pragma unroll
;     for (int a = 0; a < 2; ++a)
; #pragma unroll
;         for (int b = 0; b < 2; ++b)
; #pragma unroll
;             for (int m = 0; m < 4; ++m)
; #pragma unroll
;                 for (int n = 0; n < 2; ++n) acc[a][b][m][n] = (f32x4){0.f, 0.f, 0.f, 0.f};
;     bf16x8 At[4][2], B0[2][2], B1[2][2];
;     const char* cA = (const char*)g.A + (size_t)cur.pm * tstep + (size_t)cur.kt0 * kstep; const char* cB = (const char*)g.Bt + (size_t)cur.pn * tstep + (size_t)cur.kt0 * kstep;
;     PG8_STAGE(PG8_SB(0, 0), cB, voffB); PG8_STAGE(PG8_SA(0, 0), cA, voffA); PG8_STAGE(PG8_SB(0, 1), cB + hstep, voffB); PG8_STAGE(PG8_SA(0, 1), cA + hstep, voffA);
;     if (wr == 1) PG8_BAR;
;     PG8_WAIT_V(4); PG8_BAR;
;     PG8_STAGE(PG8_SB(1, 0), cB + kstep, voffB); PG8_STAGE(PG8_SA(1, 0), cA + kstep, voffA); PG8_STAGE(PG8_SB(1, 1), cB + hstep + kstep, voffB);
;     PG8_WAIT_V(6); PG8_BAR;
;     ...
;         if (!E.keep(cur)) {
; #pragma unroll
;             for (int a = 0; a < 2; ++a)
; #pragma unroll
;                 for (int b = 0; b < 2; ++b)
; #pragma unroll
;                     for (int m = 0; m < 4; ++m)
; #pragma unroll
;                         for (int n = 0; n < 2; ++n) acc[a][b][m][n] = (f32x4){0.f, 0.f, 0.f, 0.f};
;         }
;         nxt.rk = cur.rk + (nxt.pm != cur.pm ? 1 : 0);
;         cur = nxt; cA = nA; cB = nB; ++ui;
.LBB0_189:
	v_readlane_b32 s22, v246, 58
	v_mov_b32_e32 v161, v97
	v_readlane_b32 s23, v246, 59
	v_mov_b32_e32 v165, v97
	v_readlane_b32 s8, v247, 32
	v_lshl_add_u64 v[8:9], s[22:23], 0, v[160:161]
	v_lshl_add_u64 v[10:11], s[22:23], 0, v[164:165]
	v_mov_b32_e32 v159, v97
	v_readlane_b32 s9, v247, 33
	s_add_i32 m0, s6, 0x18000
	v_lshl_add_u64 v[8:9], v[8:9], 0, s[36:37]
	v_lshl_add_u64 v[12:13], s[8:9], 0, v[158:159]
	v_mov_b32_e32 v163, v97
	s_waitcnt vmcnt(4)
	s_barrier
	global_load_lds_dwordx4 v[8:9], off
	v_lshl_add_u64 v[8:9], v[10:11], 0, s[36:37]
	s_add_i32 m0, s6, 0x1a000
	s_add_i32 s50, s6, 0x8000
	v_lshl_add_u64 v[14:15], s[8:9], 0, v[162:163]
	global_load_lds_dwordx4 v[8:9], off
	v_lshl_add_u64 v[8:9], v[12:13], 0, s[36:37]
	s_mov_b32 m0, s50
	s_add_i32 s51, s6, 0xa000
	v_readlane_b32 s10, v246, 60
	global_load_lds_dwordx4 v[8:9], off
	v_lshl_add_u64 v[8:9], v[14:15], 0, s[36:37]
	s_mov_b32 m0, s51
	v_readlane_b32 s11, v246, 61
	global_load_lds_dwordx4 v[8:9], off
	s_add_i32 m0, s6, 0x1c000
	v_lshl_add_u64 v[8:9], s[10:11], 0, v[160:161]
	global_load_lds_dwordx4 v[8:9], off
	v_lshl_add_u64 v[8:9], s[10:11], 0, v[164:165]
	s_add_i32 m0, s6, 0x1e000
	v_bfe_u32 v169, v0, 4, 2
	global_load_lds_dwordx4 v[8:9], off
	s_and_b32 s1, s2, 3
	v_and_b32_e32 v7, 15, v0
	v_lshlrev_b32_e32 v0, 3, v169
	v_lshl_or_b32 v166, s1, 5, v0
	v_or_b32_e32 v0, 16, v7
	v_lshl_or_b32 v172, v0, 7, v232
	v_lshl_or_b32 v174, v0, 9, v233
	v_lshlrev_b32_e32 v0, 14, v1
	v_and_b32_e32 v0, 0xffff8000, v0
	v_lshl_add_u32 v0, v3, 11, v0
	v_and_b32_e32 v1, 1, v1
	v_lshl_or_b32 v171, s0, 6, v7
	s_lshl_b32 s2, s0, 13
	s_lshl_b32 s0, s0, 8
	v_lshl_or_b32 v0, v1, 6, v0
	v_lshlrev_b32_e32 v16, 4, v169
	v_lshlrev_b32_e32 v17, 2, v7
	s_add_i32 s0, s0, 0
	v_lshl_add_u32 v184, v5, 1, v0
	v_lshlrev_b32_e32 v0, 14, v2
	v_lshl_or_b32 v16, v7, 6, v16
	v_and_b32_e32 v18, 32, v17
	s_add_i32 s0, s0, 0x20040
	v_and_b32_e32 v0, 0xffff8000, v0
	v_bitop3_b32 v19, v16, s2, v18 bitop3:0xde
	s_lshl_b32 s2, s1, 12
	v_add_u32_e32 v175, s0, v17
	v_lshl_add_u32 v0, v4, 11, v0
	v_and_b32_e32 v1, 1, v2
	v_readlane_b32 s0, v247, 26
	s_waitcnt vmcnt(6)
	v_lshl_or_b32 v0, v1, 6, v0
	v_readlane_b32 s1, v247, 27
	s_bitcmp0_b32 s49, 6
	v_or_b32_e32 v8, 32, v7
	v_or_b32_e32 v9, 48, v7
	v_lshl_add_u32 v186, v6, 1, v0
	v_mov_b32_e32 v0, 0
	s_mov_b32 s96, s0
	v_readlane_b32 s0, v247, 28
	v_bitop3_b32 v173, v16, s2, v18 bitop3:0xde
	s_mov_b32 s4, 0
	s_cselect_b64 s[52:53], -1, 0
	v_or_b32_e32 v177, 0x2000, v7
	v_lshl_or_b32 v168, v7, 7, v232
	v_lshl_or_b32 v170, v7, 9, v233
	v_or_b32_e32 v179, 0x2010, v7
	v_or_b32_e32 v181, 0x2020, v7
	v_lshl_or_b32 v176, v8, 7, v232
	v_lshl_or_b32 v178, v8, 9, v233
	v_or_b32_e32 v183, 0x2030, v7
	v_lshl_or_b32 v180, v9, 7, v232
	v_lshl_or_b32 v182, v9, 9, v233
	v_mov_b32_e32 v185, v97
	v_mov_b32_e32 v187, v97
	v_add_u32_e32 v193, 0, v19
	s_mov_b32 s97, s0
	s_mov_b32 s94, 0
	s_barrier
	v_readlane_b32 s1, v247, 29
	s_branch .LBB0_191
.LBB0_190:
	s_cmp_lg_u32 s12, s96
	s_cselect_b64 s[0:1], -1, 0
	s_cmp_lg_u64 s[0:1], 0
	v_mov_b32_e32 v0, 0
	s_addc_u32 s4, s4, 0
	s_mov_b32 s96, s12
	s_mov_b32 s97, s10
	s_mov_b64 s[8:9], s[20:21]
	s_mov_b32 s94, s95
	s_andn2_b64 vcc, exec, s[14:15]
	s_mov_b64 s[22:23], s[16:17]
	s_cbranch_vccz .LBB0_791

;     DI bool next(int i, Unit& u) const { Unit p; if (!so.next(i >> 1, p)) return false; const int s = i & 1; u = p; u.pm = s * (T / BM) + p.pm; u.pn = s * 4 + p.pn; return true; }
; #define PG8_STAGE(bufoff, gbase, voff) do { _Pragma("unroll") for (int _i = 0; _i < 2; ++_i) \
;         __builtin_amdgcn_global_load_lds((const unsigned*)((const char*)(gbase) + (voff)[_i]), (LAS unsigned*)(lds + (bufoff) + ldsw + _i * 8192), 16, 0, 0); } while (0)
; #define PG8_LDA(dst, b, h) do { _Pragma("unroll") for (int m = 0; m < 4; ++m) _Pragma("unroll") for (int k = 0; k < 2; ++k) dst[m][k] = *(const LAS bf16x8*)(lds + PG8_SA(b, h) + aoff + m * 2048 + k * 1024); } while (0)
; #define PG8_LDB(dst, b, h) do { _Pragma("unroll") for (int n = 0; n < 2; ++n) _Pragma("unroll") for (int k = 0; k < 2; ++k) dst[n][k] = *(const LAS bf16x8*)(lds + PG8_SB(b, h) + boff + n * 2048 + k * 1024); } while (0)
; #define PG8_MMA(ai, bj, At, Bt) do { __builtin_amdgcn_s_setprio(1); _Pragma("unroll") for (int m = 0; m < 4; ++m) _Pragma("unroll") for (int n = 0; n < 2; ++n) _Pragma("unroll") for (int k = 0; k < 2; ++k) \
;         acc[ai][bj][m][n] = __builtin_amdgcn_mfma_f32_16x16x32_bf16(Bt[n][k], At[m][k], acc[ai][bj][m][n], 0, 0, 0); __builtin_amdgcn_s_setprio(0); } while (0)
; template <class Epi, class Sched>
; DI void gemm_phase(LAS unsigned char* lds, const Gemm g, const Sched& S, const Epi& E) {
;     ...
;         const bool has_next = S.next(ui + 1, nxt);
;         const char* nA = has_next ? (const char*)g.A + (size_t)nxt.pm * tstep + (size_t)nxt.kt0 * kstep : cA; const char* nB = has_next ? (const char*)g.Bt + (size_t)nxt.pn * tstep + (size_t)nxt.kt0 * kstep : cB;
;         const int nt = cur.nkt;
;         for (int t = 0; t < nt; t += 2) {
;             const bool last = (t == nt - 2);
;             const char* a1 = cA + (size_t)(t + 1) * kstep;
;             const char* a2 = last ? nA : cA + (size_t)(t + 2) * kstep; const char* b2 = last ? nB : cB + (size_t)(t + 2) * kstep;
;             const char* a3 = a2 + kstep; const char* b3 = b2 + kstep;
;             PG8_LDB(B0, 0, 0); PG8_SCHED; PG8_LDA(At, 0, 0); PG8_STAGE(PG8_SA(1, 1), a1 + hstep, voffA);
;             PG8_WAIT_L(8); PG8_BAR; PG8_WAIT_L(0); PG8_MMA(0, 0, At, B0); PG8_BAR; PG8_SCHED;
;             PG8_LDB(B1, 0, 1); PG8_STAGE(PG8_SB(0, 0), b2, voffB);
;             PG8_BAR; PG8_WAIT_L(0); PG8_MMA(0, 1, At, B1); PG8_BAR;
.LBB0_195:
	s_add_u32 s76, s22, 0x100
	s_addc_u32 s33, s23, 0
	s_ashr_i32 s13, s12, 31
	s_lshl_b64 s[0:1], s[12:13], 19
	s_add_u32 s20, s72, s0
	s_addc_u32 s21, s73, s1
	s_and_b64 s[0:1], s[18:19], exec
	s_cselect_b32 s2, s21, s9
	s_cselect_b32 s13, s20, s8
	s_ashr_i32 s11, s10, 31
	s_lshl_b64 s[0:1], s[10:11], 19
	v_readlane_b32 s11, v246, 54
	s_add_u32 s16, s11, s0
	v_readlane_b32 s0, v246, 55
	s_addc_u32 s17, s0, s1
	s_and_b64 s[0:1], s[18:19], exec
	s_cselect_b32 s11, s17, s23
	s_cselect_b32 s26, s16, s22
	s_add_u32 s0, s8, 0x40080
	s_addc_u32 s1, s9, 0
	v_lshl_add_u64 v[130:131], s[0:1], 0, v[184:185]
	v_lshl_add_u64 v[132:133], s[0:1], 0, v[186:187]
	s_mov_b32 s27, -2
	s_mov_b64 s[22:23], 0
	s_add_u32 s0, s8, s22
	s_addc_u32 s1, s9, s23
	s_add_u32 s0, s0, 0x100
	s_addc_u32 s1, s1, 0
	s_add_u32 s24, s76, s22
	s_addc_u32 s25, s33, s23
	s_add_i32 s28, 0, 0x10000
	v_add_u32_e32 v96, s28, v173
	ds_read_b128 v[134:137], v96
	ds_read_b128 v[138:141], v96 offset:1024
	ds_read_b128 v[142:145], v96 offset:2048
	ds_read_b128 v[146:149], v96 offset:3072
	s_cmpk_eq_i32 s22, 0x700
	s_cselect_b32 s39, s2, s1
	s_cselect_b32 s38, s13, s0
	s_cselect_b32 s25, s11, s25
	s_cselect_b32 s24, s26, s24
	v_lshl_add_u64 v[214:215], v[130:131], 0, s[22:23]
	s_add_i32 m0, s6, 0xc000
	ds_read_b128 v[150:153], v193
	ds_read_b128 v[154:157], v193 offset:1024
	s_waitcnt lgkmcnt(0)
	ds_read_b128 v[188:191], v193 offset:2048
	ds_read_b128 v[194:197], v193 offset:3072
	ds_read_b128 v[198:201], v193 offset:4096
	ds_read_b128 v[202:205], v193 offset:5120
	ds_read_b128 v[206:209], v193 offset:6144
	ds_read_b128 v[210:213], v193 offset:7168
	global_load_lds_dwordx4 v[214:215], off
	v_lshl_add_u64 v[214:215], v[132:133], 0, s[22:23]
	s_add_i32 m0, s6, 0xe000
	s_nop 0
	global_load_lds_dwordx4 v[214:215], off
	s_waitcnt lgkmcnt(8)
	s_barrier
	s_waitcnt lgkmcnt(0)
	s_setprio 1
	s_waitcnt lgkmcnt(0)
	v_mfma_f32_16x16x32_bf16 v[126:129], v[134:137], v[150:153], 0
	v_mfma_f32_16x16x32_bf16 v[122:125], v[142:145], v[150:153], 0
	v_mfma_f32_16x16x32_bf16 v[118:121], v[134:137], v[188:191], 0
	v_mfma_f32_16x16x32_bf16 v[114:117], v[142:145], v[188:191], 0
	v_mfma_f32_16x16x32_bf16 v[110:113], v[134:137], v[198:201], 0
	v_mfma_f32_16x16x32_bf16 v[106:109], v[142:145], v[198:201], 0
	v_mfma_f32_16x16x32_bf16 v[102:105], v[134:137], v[206:209], 0
	v_mfma_f32_16x16x32_bf16 v[98:101], v[142:145], v[206:209], 0
	v_mfma_f32_16x16x32_bf16 v[126:129], v[138:141], v[154:157], v[126:129]
	v_mfma_f32_16x16x32_bf16 v[122:125], v[146:149], v[154:157], v[122:125]
	v_mfma_f32_16x16x32_bf16 v[118:121], v[138:141], v[194:197], v[118:121]
	v_mfma_f32_16x16x32_bf16 v[114:117], v[146:149], v[194:197], v[114:117]
	v_mfma_f32_16x16x32_bf16 v[110:113], v[138:141], v[202:205], v[110:113]
	v_mfma_f32_16x16x32_bf16 v[106:109], v[146:149], v[202:205], v[106:109]
	v_mfma_f32_16x16x32_bf16 v[102:105], v[138:141], v[210:213], v[102:105]
	v_mfma_f32_16x16x32_bf16 v[98:101], v[146:149], v[210:213], v[98:101]
	s_setprio 0
	s_barrier
	s_add_i32 s29, 0, 0x14000
	s_add_i32 s0, s28, s68
	v_add_u32_e32 v96, s29, v173
	v_lshl_add_u64 v[226:227], s[24:25], 0, v[160:161]
	s_mov_b32 m0, s0
	ds_read_b128 v[214:217], v96
	ds_read_b128 v[218:221], v96 offset:1024
	ds_read_b128 v[222:225], v96 offset:2048
	ds_read_b128 v[236:239], v96 offset:3072
	global_load_lds_dwordx4 v[226:227], off
	v_lshl_add_u64 v[240:241], s[24:25], 0, v[164:165]
	s_add_i32 m0, s0, 0x2000
	s_nop 0
	global_load_lds_dwordx4 v[240:241], off
	s_barrier
; #define PG8_STAGE(bufoff, gbase, voff) do { _Pragma("unroll") for (int _i = 0; _i < 2; ++_i) \
;         __builtin_amdgcn_global_load_lds((const unsigned*)((const char*)(gbase) + (voff)[_i]), (LAS unsigned*)(lds + (bufoff) + ldsw + _i * 8192), 16, 0, 0); } while (0)
; #define PG8_LDA(dst, b, h) do { _Pragma("unroll") for (int m = 0; m < 4; ++m) _Pragma("unroll") for (int k = 0; k < 2; ++k) dst[m][k] = *(const LAS bf16x8*)(lds + PG8_SA(b, h) + aoff + m * 2048 + k * 1024); } while (0)
; #define PG8_MMA(ai, bj, At, Bt) do { __builtin_amdgcn_s_setprio(1); _Pragma("unroll") for (int m = 0; m < 4; ++m) _Pragma("unroll") for (int n = 0; n < 2; ++n) _Pragma("unroll") for (int k = 0; k < 2; ++k) \
;         acc[ai][bj][m][n] = __builtin_amdgcn_mfma_f32_16x16x32_bf16(Bt[n][k], At[m][k], acc[ai][bj][m][n], 0, 0, 0); __builtin_amdgcn_s_setprio(0); } while (0)
; #define PG8_WAIT_V(n) asm volatile("s_waitcnt vmcnt(" #n ")" ::: "memory")
; #define PG8_WAIT_L(n) asm volatile("s_waitcnt lgkmcnt(" #n ")" ::: "memory")
; #define PG8_BAR __builtin_amdgcn_s_barrier()
; #define PG8_SCHED __builtin_amdgcn_sched_barrier(0)
; template <class Epi, class Sched>
; DI void gemm_phase(LAS unsigned char* lds, const Gemm g, const Sched& S, const Epi& E) {
;     ...
;             PG8_BAR; PG8_WAIT_L(0); PG8_MMA(0, 1, At, B1); PG8_BAR;
;             PG8_LDA(At, 0, 1); PG8_STAGE(PG8_SA(0, 0), a2, voffA);
;             PG8_BAR; PG8_WAIT_L(0); PG8_MMA(1, 0, At, B0); PG8_BAR; PG8_SCHED;
;             PG8_STAGE(PG8_SB(0, 1), b2 + hstep, voffB);
;             PG8_WAIT_V(6); PG8_BAR; PG8_MMA(1, 1, At, B1); PG8_BAR;
	s_waitcnt lgkmcnt(0)
	s_setprio 1
	s_waitcnt lgkmcnt(0)
	v_mfma_f32_16x16x32_bf16 v[92:95], v[214:217], v[150:153], 0
	v_mfma_f32_16x16x32_bf16 v[88:91], v[222:225], v[150:153], 0
	v_mfma_f32_16x16x32_bf16 v[84:87], v[214:217], v[188:191], 0
	v_mfma_f32_16x16x32_bf16 v[80:83], v[222:225], v[188:191], 0
	v_mfma_f32_16x16x32_bf16 v[76:79], v[214:217], v[198:201], 0
	v_mfma_f32_16x16x32_bf16 v[72:75], v[222:225], v[198:201], 0
	v_mfma_f32_16x16x32_bf16 v[68:71], v[214:217], v[206:209], 0
	v_mfma_f32_16x16x32_bf16 v[64:67], v[222:225], v[206:209], 0
	v_mfma_f32_16x16x32_bf16 v[92:95], v[218:221], v[154:157], v[92:95]
	v_mfma_f32_16x16x32_bf16 v[88:91], v[236:239], v[154:157], v[88:91]
	v_mfma_f32_16x16x32_bf16 v[84:87], v[218:221], v[194:197], v[84:87]
	v_mfma_f32_16x16x32_bf16 v[80:83], v[236:239], v[194:197], v[80:83]
	v_mfma_f32_16x16x32_bf16 v[76:79], v[218:221], v[202:205], v[76:79]
	v_mfma_f32_16x16x32_bf16 v[72:75], v[236:239], v[202:205], v[72:75]
	v_mfma_f32_16x16x32_bf16 v[68:71], v[218:221], v[210:213], v[68:71]
	v_mfma_f32_16x16x32_bf16 v[64:67], v[236:239], v[210:213], v[64:67]
	s_setprio 0
	s_mov_b32 m0, s6
	v_lshl_add_u64 v[242:243], s[38:39], 0, v[158:159]
	s_barrier
	ds_read_b128 v[150:153], v193 offset:16384
	ds_read_b128 v[154:157], v193 offset:17408
	ds_read_b128 v[188:191], v193 offset:18432
	ds_read_b128 v[194:197], v193 offset:19456
	ds_read_b128 v[198:201], v193 offset:20480
	ds_read_b128 v[202:205], v193 offset:21504
	ds_read_b128 v[206:209], v193 offset:22528
	ds_read_b128 v[210:213], v193 offset:23552
	global_load_lds_dwordx4 v[242:243], off
	v_lshl_add_u64 v[244:245], s[38:39], 0, v[162:163]
	s_mov_b32 m0, s7
	s_nop 0
	global_load_lds_dwordx4 v[244:245], off
	s_barrier
	s_waitcnt lgkmcnt(0)
	s_setprio 1
	s_waitcnt lgkmcnt(0)
	v_mfma_f32_16x16x32_bf16 v[60:63], v[134:137], v[150:153], 0
	v_mfma_f32_16x16x32_bf16 v[56:59], v[142:145], v[150:153], 0
	v_mfma_f32_16x16x32_bf16 v[52:55], v[134:137], v[188:191], 0
	v_mfma_f32_16x16x32_bf16 v[48:51], v[142:145], v[188:191], 0
	v_mfma_f32_16x16x32_bf16 v[44:47], v[134:137], v[198:201], 0
	v_mfma_f32_16x16x32_bf16 v[40:43], v[142:145], v[198:201], 0
	v_mfma_f32_16x16x32_bf16 v[36:39], v[134:137], v[206:209], 0
	v_mfma_f32_16x16x32_bf16 v[32:35], v[142:145], v[206:209], 0
	v_mfma_f32_16x16x32_bf16 v[60:63], v[138:141], v[154:157], v[60:63]
	v_mfma_f32_16x16x32_bf16 v[56:59], v[146:149], v[154:157], v[56:59]
	v_mfma_f32_16x16x32_bf16 v[52:55], v[138:141], v[194:197], v[52:55]
	v_mfma_f32_16x16x32_bf16 v[48:51], v[146:149], v[194:197], v[48:51]
	v_mfma_f32_16x16x32_bf16 v[44:47], v[138:141], v[202:205], v[44:47]
	v_mfma_f32_16x16x32_bf16 v[40:43], v[146:149], v[202:205], v[40:43]
	v_mfma_f32_16x16x32_bf16 v[36:39], v[138:141], v[210:213], v[36:39]
	v_mfma_f32_16x16x32_bf16 v[32:35], v[146:149], v[210:213], v[32:35]
	s_setprio 0
	s_barrier
	s_add_u32 s0, s24, 0x40000
	s_addc_u32 s1, s25, 0
	s_add_i32 s28, s29, s68
	v_lshl_add_u64 v[134:135], s[0:1], 0, v[160:161]
	s_mov_b32 m0, s28
	s_nop 0
	global_load_lds_dwordx4 v[134:135], off
	v_lshl_add_u64 v[134:135], s[0:1], 0, v[164:165]
	s_add_i32 m0, s28, 0x2000
	s_nop 0
	global_load_lds_dwordx4 v[134:135], off
	s_waitcnt vmcnt(6)
	s_barrier
	s_setprio 1
	v_mfma_f32_16x16x32_bf16 v[28:31], v[214:217], v[150:153], 0
	v_mfma_f32_16x16x32_bf16 v[24:27], v[222:225], v[150:153], 0
	v_mfma_f32_16x16x32_bf16 v[20:23], v[214:217], v[188:191], 0
	v_mfma_f32_16x16x32_bf16 v[16:19], v[222:225], v[188:191], 0
	v_mfma_f32_16x16x32_bf16 v[12:15], v[214:217], v[198:201], 0
	v_mfma_f32_16x16x32_bf16 v[8:11], v[222:225], v[198:201], 0
	v_mfma_f32_16x16x32_bf16 v[4:7], v[214:217], v[206:209], 0
	v_mfma_f32_16x16x32_bf16 v[0:3], v[222:225], v[206:209], 0
	v_mfma_f32_16x16x32_bf16 v[28:31], v[218:221], v[154:157], v[28:31]
	v_mfma_f32_16x16x32_bf16 v[24:27], v[236:239], v[154:157], v[24:27]
	v_mfma_f32_16x16x32_bf16 v[20:23], v[218:221], v[194:197], v[20:23]
	v_mfma_f32_16x16x32_bf16 v[16:19], v[236:239], v[194:197], v[16:19]
	v_mfma_f32_16x16x32_bf16 v[12:15], v[218:221], v[202:205], v[12:15]
	v_mfma_f32_16x16x32_bf16 v[8:11], v[236:239], v[202:205], v[8:11]
	v_mfma_f32_16x16x32_bf16 v[4:7], v[218:221], v[210:213], v[4:7]
	v_mfma_f32_16x16x32_bf16 v[0:3], v[236:239], v[210:213], v[0:3]
	s_setprio 0
	s_branch .Lkmid_4293

; #define PG8_STAGE(bufoff, gbase, voff) do { _Pragma("unroll") for (int _i = 0; _i < 2; ++_i) \
;         __builtin_amdgcn_global_load_lds((const unsigned*)((const char*)(gbase) + (voff)[_i]), (LAS unsigned*)(lds + (bufoff) + ldsw + _i * 8192), 16, 0, 0); } while (0)
; #define PG8_LDA(dst, b, h) do { _Pragma("unroll") for (int m = 0; m < 4; ++m) _Pragma("unroll") for (int k = 0; k < 2; ++k) dst[m][k] = *(const LAS bf16x8*)(lds + PG8_SA(b, h) + aoff + m * 2048 + k * 1024); } while (0)
; #define PG8_LDB(dst, b, h) do { _Pragma("unroll") for (int n = 0; n < 2; ++n) _Pragma("unroll") for (int k = 0; k < 2; ++k) dst[n][k] = *(const LAS bf16x8*)(lds + PG8_SB(b, h) + boff + n * 2048 + k * 1024); } while (0)
; #define PG8_MMA(ai, bj, At, Bt) do { __builtin_amdgcn_s_setprio(1); _Pragma("unroll") for (int m = 0; m < 4; ++m) _Pragma("unroll") for (int n = 0; n < 2; ++n) _Pragma("unroll") for (int k = 0; k < 2; ++k) \
;         acc[ai][bj][m][n] = __builtin_amdgcn_mfma_f32_16x16x32_bf16(Bt[n][k], At[m][k], acc[ai][bj][m][n], 0, 0, 0); __builtin_amdgcn_s_setprio(0); } while (0)
; #define PG8_WAIT_L(n) asm volatile("s_waitcnt lgkmcnt(" #n ")" ::: "memory")
; #define PG8_BAR __builtin_amdgcn_s_barrier()
; #define PG8_SCHED __builtin_amdgcn_sched_barrier(0)
; template <class Epi, class Sched>
; DI void gemm_phase(LAS unsigned char* lds, const Gemm g, const Sched& S, const Epi& E) {
;     ...
;             PG8_LDB(B0, 1, 0); PG8_SCHED; PG8_LDA(At, 1, 0); PG8_STAGE(PG8_SA(0, 1), a2 + hstep, voffA);
;             PG8_WAIT_L(8); PG8_BAR; PG8_WAIT_L(0); PG8_MMA(0, 0, At, B0); PG8_BAR; PG8_SCHED;
;             PG8_LDB(B1, 1, 1); PG8_STAGE(PG8_SB(1, 0), b3, voffB);
;             PG8_BAR; PG8_WAIT_L(0); PG8_MMA(0, 1, At, B1); PG8_BAR;
;             PG8_LDA(At, 1, 1); PG8_STAGE(PG8_SA(1, 0), a3, voffA);
;             PG8_BAR; PG8_WAIT_L(0); PG8_MMA(1, 0, At, B0); PG8_BAR; PG8_SCHED;
.Lkmid_4293:
	s_add_i32 s28, 0, 0x18000
	v_add_u32_e32 v96, s28, v173
	s_barrier
	ds_read_b128 v[134:137], v96
	ds_read_b128 v[138:141], v96 offset:1024
	ds_read_b128 v[142:145], v96 offset:2048
	ds_read_b128 v[146:149], v96 offset:3072
	s_add_u32 s0, s38, 0x40000
	s_addc_u32 s1, s39, 0
	s_mov_b32 m0, s5
	v_lshl_add_u64 v[214:215], s[0:1], 0, v[158:159]
	ds_read_b128 v[150:153], v193 offset:32768
	ds_read_b128 v[154:157], v193 offset:33792
	ds_read_b128 v[188:191], v193 offset:34816
	ds_read_b128 v[194:197], v193 offset:35840
	ds_read_b128 v[198:201], v193 offset:36864
	ds_read_b128 v[202:205], v193 offset:37888
	ds_read_b128 v[206:209], v193 offset:38912
	ds_read_b128 v[210:213], v193 offset:39936
	global_load_lds_dwordx4 v[214:215], off
	v_lshl_add_u64 v[214:215], s[0:1], 0, v[162:163]
	s_mov_b32 m0, s93
	s_nop 0
	global_load_lds_dwordx4 v[214:215], off
	s_waitcnt lgkmcnt(8)
	s_barrier
	s_waitcnt lgkmcnt(0)
	s_setprio 1
	s_waitcnt lgkmcnt(0)
	v_mfma_f32_16x16x32_bf16 v[126:129], v[134:137], v[150:153], v[126:129]
	v_mfma_f32_16x16x32_bf16 v[122:125], v[142:145], v[150:153], v[122:125]
	v_mfma_f32_16x16x32_bf16 v[118:121], v[134:137], v[188:191], v[118:121]
	v_mfma_f32_16x16x32_bf16 v[114:117], v[142:145], v[188:191], v[114:117]
	v_mfma_f32_16x16x32_bf16 v[110:113], v[134:137], v[198:201], v[110:113]
	v_mfma_f32_16x16x32_bf16 v[106:109], v[142:145], v[198:201], v[106:109]
	v_mfma_f32_16x16x32_bf16 v[102:105], v[134:137], v[206:209], v[102:105]
	v_mfma_f32_16x16x32_bf16 v[98:101], v[142:145], v[206:209], v[98:101]
	v_mfma_f32_16x16x32_bf16 v[126:129], v[138:141], v[154:157], v[126:129]
	v_mfma_f32_16x16x32_bf16 v[122:125], v[146:149], v[154:157], v[122:125]
	v_mfma_f32_16x16x32_bf16 v[118:121], v[138:141], v[194:197], v[118:121]
	v_mfma_f32_16x16x32_bf16 v[114:117], v[146:149], v[194:197], v[114:117]
	v_mfma_f32_16x16x32_bf16 v[110:113], v[138:141], v[202:205], v[110:113]
	v_mfma_f32_16x16x32_bf16 v[106:109], v[146:149], v[202:205], v[106:109]
	v_mfma_f32_16x16x32_bf16 v[102:105], v[138:141], v[210:213], v[102:105]
	v_mfma_f32_16x16x32_bf16 v[98:101], v[146:149], v[210:213], v[98:101]
	s_setprio 0
	s_barrier
	s_add_i32 s29, 0, 0x1c000
	s_add_i32 s0, s28, s68
	v_add_u32_e32 v96, s29, v173
	v_lshl_add_u64 v[226:227], v[226:227], 0, s[36:37]
	s_mov_b32 m0, s0
	ds_read_b128 v[214:217], v96
	ds_read_b128 v[218:221], v96 offset:1024
	ds_read_b128 v[222:225], v96 offset:2048
	ds_read_b128 v[236:239], v96 offset:3072
	global_load_lds_dwordx4 v[226:227], off
	v_lshl_add_u64 v[226:227], v[240:241], 0, s[36:37]
	s_add_i32 m0, s0, 0x2000
	s_nop 0
	global_load_lds_dwordx4 v[226:227], off
	s_barrier
	s_waitcnt lgkmcnt(0)
	s_setprio 1
	s_waitcnt lgkmcnt(0)
	v_mfma_f32_16x16x32_bf16 v[92:95], v[214:217], v[150:153], v[92:95]
	v_mfma_f32_16x16x32_bf16 v[88:91], v[222:225], v[150:153], v[88:91]
	v_mfma_f32_16x16x32_bf16 v[84:87], v[214:217], v[188:191], v[84:87]
	v_mfma_f32_16x16x32_bf16 v[80:83], v[222:225], v[188:191], v[80:83]
	v_mfma_f32_16x16x32_bf16 v[76:79], v[214:217], v[198:201], v[76:79]
	v_mfma_f32_16x16x32_bf16 v[72:75], v[222:225], v[198:201], v[72:75]
	v_mfma_f32_16x16x32_bf16 v[68:71], v[214:217], v[206:209], v[68:71]
	v_mfma_f32_16x16x32_bf16 v[64:67], v[222:225], v[206:209], v[64:67]
	v_mfma_f32_16x16x32_bf16 v[92:95], v[218:221], v[154:157], v[92:95]
	v_mfma_f32_16x16x32_bf16 v[88:91], v[236:239], v[154:157], v[88:91]
	v_mfma_f32_16x16x32_bf16 v[84:87], v[218:221], v[194:197], v[84:87]
	v_mfma_f32_16x16x32_bf16 v[80:83], v[236:239], v[194:197], v[80:83]
	v_mfma_f32_16x16x32_bf16 v[76:79], v[218:221], v[202:205], v[76:79]
	v_mfma_f32_16x16x32_bf16 v[72:75], v[236:239], v[202:205], v[72:75]
	v_mfma_f32_16x16x32_bf16 v[68:71], v[218:221], v[210:213], v[68:71]
	v_mfma_f32_16x16x32_bf16 v[64:67], v[236:239], v[210:213], v[64:67]
	s_setprio 0
	s_mov_b32 m0, s50
	v_lshl_add_u64 v[226:227], v[242:243], 0, s[36:37]
	s_barrier
; #define PG8_STAGE(bufoff, gbase, voff) do { _Pragma("unroll") for (int _i = 0; _i < 2; ++_i) \
;         __builtin_amdgcn_global_load_lds((const unsigned*)((const char*)(gbase) + (voff)[_i]), (LAS unsigned*)(lds + (bufoff) + ldsw + _i * 8192), 16, 0, 0); } while (0)
; #define PG8_LDA(dst, b, h) do { _Pragma("unroll") for (int m = 0; m < 4; ++m) _Pragma("unroll") for (int k = 0; k < 2; ++k) dst[m][k] = *(const LAS bf16x8*)(lds + PG8_SA(b, h) + aoff + m * 2048 + k * 1024); } while (0)
; #define PG8_LDB(dst, b, h) do { _Pragma("unroll") for (int n = 0; n < 2; ++n) _Pragma("unroll") for (int k = 0; k < 2; ++k) dst[n][k] = *(const LAS bf16x8*)(lds + PG8_SB(b, h) + boff + n * 2048 + k * 1024); } while (0)
; #define PG8_WAIT_V(n) asm volatile("s_waitcnt vmcnt(" #n ")" ::: "memory")
; #define PG8_WAIT_L(n) asm volatile("s_waitcnt lgkmcnt(" #n ")" ::: "memory")
; #define PG8_BAR __builtin_amdgcn_s_barrier()
; #define PG8_SCHED __builtin_amdgcn_sched_barrier(0)
; template <class Epi, class Sched>
; DI void gemm_phase(LAS unsigned char* lds, const Gemm g, const Sched& S, const Epi& E) {
;     ...
;             PG8_LDB(B0, 0, 0); PG8_SCHED; PG8_LDA(At, 0, 0); PG8_STAGE(PG8_SA(1, 1), a1 + hstep, voffA);
;             PG8_WAIT_L(8); PG8_BAR; PG8_WAIT_L(0); PG8_MMA(0, 0, At, B0); PG8_BAR; PG8_SCHED;
;             PG8_LDB(B1, 0, 1); PG8_STAGE(PG8_SB(0, 0), b2, voffB);
;             PG8_BAR; PG8_WAIT_L(0); PG8_MMA(0, 1, At, B1); PG8_BAR;
;             PG8_LDA(At, 0, 1); PG8_STAGE(PG8_SA(0, 0), a2, voffA);
;             PG8_BAR; PG8_WAIT_L(0); PG8_MMA(1, 0, At, B0); PG8_BAR; PG8_SCHED;
;             PG8_STAGE(PG8_SB(0, 1), b2 + hstep, voffB);
;             PG8_WAIT_V(6); PG8_BAR; PG8_MMA(1, 1, At, B1); PG8_BAR;
;             PG8_LDB(B0, 1, 0); PG8_SCHED; PG8_LDA(At, 1, 0); PG8_STAGE(PG8_SA(0, 1), a2 + hstep, voffA);
;             PG8_WAIT_L(8); PG8_BAR; PG8_WAIT_L(0); PG8_MMA(0, 0, At, B0); PG8_BAR; PG8_SCHED;
;             PG8_LDB(B1, 1, 1); PG8_STAGE(PG8_SB(1, 0), b3, voffB);
;             PG8_BAR; PG8_WAIT_L(0); PG8_MMA(0, 1, At, B1); PG8_BAR;
;             PG8_LDA(At, 1, 1); PG8_STAGE(PG8_SA(1, 0), a3, voffA);
;             PG8_BAR; PG8_WAIT_L(0); PG8_MMA(1, 0, At, B0); PG8_BAR; PG8_SCHED;
;             PG8_STAGE(PG8_SB(1, 1), b3 + hstep, voffB);
;             PG8_WAIT_V(6); PG8_BAR; PG8_MMA(1, 1, At, B1); PG8_BAR;
	ds_read_b128 v[150:153], v193 offset:49152
	ds_read_b128 v[154:157], v193 offset:50176
	ds_read_b128 v[188:191], v193 offset:51200
	ds_read_b128 v[194:197], v193 offset:52224
	ds_read_b128 v[198:201], v193 offset:53248
	ds_read_b128 v[202:205], v193 offset:54272
	ds_read_b128 v[206:209], v193 offset:55296
	ds_read_b128 v[210:213], v193 offset:56320
	global_load_lds_dwordx4 v[226:227], off
	v_lshl_add_u64 v[226:227], v[244:245], 0, s[36:37]
	s_mov_b32 m0, s51
	s_nop 0
	global_load_lds_dwordx4 v[226:227], off
	s_barrier
	s_waitcnt lgkmcnt(0)
	s_setprio 1
	s_waitcnt lgkmcnt(0)
	v_mfma_f32_16x16x32_bf16 v[60:63], v[134:137], v[150:153], v[60:63]
	v_mfma_f32_16x16x32_bf16 v[56:59], v[142:145], v[150:153], v[56:59]
	v_mfma_f32_16x16x32_bf16 v[52:55], v[134:137], v[188:191], v[52:55]
	v_mfma_f32_16x16x32_bf16 v[48:51], v[142:145], v[188:191], v[48:51]
	v_mfma_f32_16x16x32_bf16 v[44:47], v[134:137], v[198:201], v[44:47]
	v_mfma_f32_16x16x32_bf16 v[40:43], v[142:145], v[198:201], v[40:43]
	v_mfma_f32_16x16x32_bf16 v[36:39], v[134:137], v[206:209], v[36:39]
	v_mfma_f32_16x16x32_bf16 v[32:35], v[142:145], v[206:209], v[32:35]
	v_mfma_f32_16x16x32_bf16 v[60:63], v[138:141], v[154:157], v[60:63]
	v_mfma_f32_16x16x32_bf16 v[56:59], v[146:149], v[154:157], v[56:59]
	v_mfma_f32_16x16x32_bf16 v[52:55], v[138:141], v[194:197], v[52:55]
	v_mfma_f32_16x16x32_bf16 v[48:51], v[146:149], v[194:197], v[48:51]
	v_mfma_f32_16x16x32_bf16 v[44:47], v[138:141], v[202:205], v[44:47]
	v_mfma_f32_16x16x32_bf16 v[40:43], v[146:149], v[202:205], v[40:43]
	v_mfma_f32_16x16x32_bf16 v[36:39], v[138:141], v[210:213], v[36:39]
	v_mfma_f32_16x16x32_bf16 v[32:35], v[146:149], v[210:213], v[32:35]
	s_setprio 0
	s_barrier
	s_add_u32 s0, s24, 0x40080
	s_addc_u32 s1, s25, 0
	s_add_i32 s24, s29, s68
	v_lshl_add_u64 v[134:135], s[0:1], 0, v[160:161]
	s_mov_b32 m0, s24
	s_nop 0
	global_load_lds_dwordx4 v[134:135], off
	v_lshl_add_u64 v[134:135], s[0:1], 0, v[164:165]
	s_add_i32 m0, s24, 0x2000
	s_nop 0
	global_load_lds_dwordx4 v[134:135], off
	s_waitcnt vmcnt(6)
	s_barrier
	s_setprio 1
	v_mfma_f32_16x16x32_bf16 v[28:31], v[214:217], v[150:153], v[28:31]
	v_mfma_f32_16x16x32_bf16 v[24:27], v[222:225], v[150:153], v[24:27]
	v_mfma_f32_16x16x32_bf16 v[20:23], v[214:217], v[188:191], v[20:23]
	v_mfma_f32_16x16x32_bf16 v[16:19], v[222:225], v[188:191], v[16:19]
	v_mfma_f32_16x16x32_bf16 v[12:15], v[214:217], v[198:201], v[12:15]
	v_mfma_f32_16x16x32_bf16 v[8:11], v[222:225], v[198:201], v[8:11]
	v_mfma_f32_16x16x32_bf16 v[4:7], v[214:217], v[206:209], v[4:7]
	v_mfma_f32_16x16x32_bf16 v[0:3], v[222:225], v[206:209], v[0:3]
	v_mfma_f32_16x16x32_bf16 v[28:31], v[218:221], v[154:157], v[28:31]
	v_mfma_f32_16x16x32_bf16 v[24:27], v[236:239], v[154:157], v[24:27]
	v_mfma_f32_16x16x32_bf16 v[20:23], v[218:221], v[194:197], v[20:23]
	v_mfma_f32_16x16x32_bf16 v[16:19], v[236:239], v[194:197], v[16:19]
	v_mfma_f32_16x16x32_bf16 v[12:15], v[218:221], v[202:205], v[12:15]
	v_mfma_f32_16x16x32_bf16 v[8:11], v[236:239], v[202:205], v[8:11]
	v_mfma_f32_16x16x32_bf16 v[4:7], v[218:221], v[210:213], v[4:7]
	v_mfma_f32_16x16x32_bf16 v[0:3], v[236:239], v[210:213], v[0:3]
	s_setprio 0
	s_add_i32 s27, s27, 2
	s_add_u32 s22, s22, 0x100
	s_addc_u32 s23, s23, 0
	s_cmp_lt_u32 s27, 14
	s_barrier
	s_cbranch_scc1 .LBB0_196
	s_cmp_lt_i32 s97, 3
	s_cbranch_scc0 .Lrope_pre_skip
	s_and_b32 s0, s96, 31
	s_lshl_b32 s0, s0, 14
	s_cmpk_lt_i32 s96, 0x80
	s_cselect_b32 s0, s0, 0x80000
	s_add_u32 s0, s82, s0
	s_addc_u32 s1, s83, 0
	v_lshl_add_u32 v216, v229, 4, s6
	v_mov_b32_e32 v217, 0
	v_lshl_add_u64 v[214:215], s[0:1], 0, v[216:217]
	s_add_i32 m0, s6, 0xc000
	s_add_u32 s0, s0, 0x2000
	s_addc_u32 s1, s1, 0
	global_load_lds_dwordx4 v[214:215], off
	v_lshl_add_u64 v[214:215], s[0:1], 0, v[216:217]
	s_add_i32 m0, s6, 0xe000
	s_nop 0
	global_load_lds_dwordx4 v[214:215], off
	s_waitcnt vmcnt(0)
	s_barrier
	s_barrier

; #define PG8_STAGE(bufoff, gbase, voff) do { _Pragma("unroll") for (int _i = 0; _i < 2; ++_i) \
;         __builtin_amdgcn_global_load_lds((const unsigned*)((const char*)(gbase) + (voff)[_i]), (LAS unsigned*)(lds + (bufoff) + ldsw + _i * 8192), 16, 0, 0); } while (0)
; #define PG8_LDA(dst, b, h) do { _Pragma("unroll") for (int m = 0; m < 4; ++m) _Pragma("unroll") for (int k = 0; k < 2; ++k) dst[m][k] = *(const LAS bf16x8*)(lds + PG8_SA(b, h) + aoff + m * 2048 + k * 1024); } while (0)
; #define PG8_LDB(dst, b, h) do { _Pragma("unroll") for (int n = 0; n < 2; ++n) _Pragma("unroll") for (int k = 0; k < 2; ++k) dst[n][k] = *(const LAS bf16x8*)(lds + PG8_SB(b, h) + boff + n * 2048 + k * 1024); } while (0)
; #define PG8_MMA(ai, bj, At, Bt) do { __builtin_amdgcn_s_setprio(1); _Pragma("unroll") for (int m = 0; m < 4; ++m) _Pragma("unroll") for (int n = 0; n < 2; ++n) _Pragma("unroll") for (int k = 0; k < 2; ++k) \
;         acc[ai][bj][m][n] = __builtin_amdgcn_mfma_f32_16x16x32_bf16(Bt[n][k], At[m][k], acc[ai][bj][m][n], 0, 0, 0); __builtin_amdgcn_s_setprio(0); } while (0)
; #define PG8_WAIT_L(n) asm volatile("s_waitcnt lgkmcnt(" #n ")" ::: "memory")
; template <class Epi, class Sched>
; DI void gemm_phase(LAS unsigned char* lds, const Gemm g, const Sched& S, const Epi& E) {
;     ...
;         const char* nA = has_next ? (const char*)g.A + (size_t)nxt.pm * tstep + (size_t)nxt.kt0 * kstep : cA; const char* nB = has_next ? (const char*)g.Bt + (size_t)nxt.pn * tstep + (size_t)nxt.kt0 * kstep : cB;
;         const int nt = cur.nkt;
;         for (int t = 0; t < nt; t += 2) {
;             const bool last = (t == nt - 2);
;             const char* a1 = cA + (size_t)(t + 1) * kstep;
;             const char* a2 = last ? nA : cA + (size_t)(t + 2) * kstep; const char* b2 = last ? nB : cB + (size_t)(t + 2) * kstep;
;             const char* a3 = a2 + kstep; const char* b3 = b2 + kstep;
;             PG8_LDB(B0, 0, 0); PG8_SCHED; PG8_LDA(At, 0, 0); PG8_STAGE(PG8_SA(1, 1), a1 + hstep, voffA);
;             PG8_WAIT_L(8); PG8_BAR; PG8_WAIT_L(0); PG8_MMA(0, 0, At, B0); PG8_BAR; PG8_SCHED;
;             PG8_LDB(B1, 0, 1); PG8_STAGE(PG8_SB(0, 0), b2, voffB);
;             PG8_BAR; PG8_WAIT_L(0); PG8_MMA(0, 1, At, B1); PG8_BAR;
;             PG8_LDA(At, 0, 1); PG8_STAGE(PG8_SA(0, 0), a2, voffA);
;             PG8_BAR; PG8_WAIT_L(0); PG8_MMA(1, 0, At, B0); PG8_BAR; PG8_SCHED;
.LBB0_1683:
	s_ashr_i32 s11, s10, 31
	s_xor_b64 s[14:15], s[22:23], -1
	s_lshl_b64 s[0:1], s[10:11], 19
	s_add_u32 s12, s74, s0
	s_addc_u32 s13, s75, s1
	s_and_b64 s[0:1], s[22:23], exec
	s_cselect_b32 s11, s13, s19
	s_cselect_b32 s31, s12, s18
	s_ashr_i32 s9, s8, 31
	s_lshl_b64 s[0:1], s[8:9], 19
	v_readlane_b32 s9, v235, 6
	s_add_u32 s16, s9, s0
	v_readlane_b32 s0, v235, 7
	s_addc_u32 s17, s0, s1
	s_and_b64 s[0:1], s[22:23], exec
	s_cselect_b32 s9, s17, s21
	s_cselect_b32 s33, s16, s20
	s_add_u32 s18, s18, 0x40080
	s_addc_u32 s19, s19, 0
	s_add_u32 s34, s20, 0x100
	v_mov_b32_e32 v0, 0
	s_addc_u32 s40, s21, 0
	s_mov_b32 s41, -2
	s_waitcnt lgkmcnt(0)
	s_waitcnt lgkmcnt(0)
	s_waitcnt vmcnt(0)
	s_add_u32 s0, s18, 0xfffc0080
	s_addc_u32 s1, s19, -1
	s_add_i32 s42, 0, 0x10000
	v_add_u32_e32 v142, s42, v198
	ds_read_b128 v[130:133], v142
	ds_read_b128 v[134:137], v142 offset:1024
	ds_read_b128 v[138:141], v142 offset:2048
	ds_read_b128 v[142:145], v142 offset:3072
	s_cmp_eq_u32 s41, 12
	s_cselect_b32 s23, s11, s1
	s_cselect_b32 s22, s31, s0
	s_cselect_b32 s21, s9, s40
	s_cselect_b32 s20, s33, s34
	v_lshl_add_u64 v[184:185], s[18:19], 0, v[180:181]
	s_add_i32 m0, s6, 0xc000
	ds_read_b128 v[146:149], v200
	ds_read_b128 v[150:153], v200 offset:1024
	ds_read_b128 v[154:157], v200 offset:2048
	ds_read_b128 v[158:161], v200 offset:3072
	ds_read_b128 v[162:165], v200 offset:4096
	ds_read_b128 v[166:169], v200 offset:5120
	ds_read_b128 v[170:173], v200 offset:6144
	ds_read_b128 v[174:177], v200 offset:7168
	global_load_lds_dwordx4 v[184:185], off
	v_lshl_add_u64 v[184:185], s[18:19], 0, v[182:183]
	s_add_i32 m0, s6, 0xe000
	s_nop 0
	global_load_lds_dwordx4 v[184:185], off
	s_waitcnt lgkmcnt(8)
	s_barrier
	s_waitcnt lgkmcnt(0)
	s_setprio 1
	s_waitcnt lgkmcnt(0)
	v_mfma_f32_16x16x32_bf16 v[126:129], v[130:133], v[146:149], 0
	v_mfma_f32_16x16x32_bf16 v[122:125], v[138:141], v[146:149], 0
	v_mfma_f32_16x16x32_bf16 v[110:113], v[130:133], v[154:157], 0
	v_mfma_f32_16x16x32_bf16 v[106:109], v[138:141], v[154:157], 0
	v_mfma_f32_16x16x32_bf16 v[92:95], v[130:133], v[162:165], 0
	v_mfma_f32_16x16x32_bf16 v[88:91], v[138:141], v[162:165], 0
	v_mfma_f32_16x16x32_bf16 v[76:79], v[130:133], v[170:173], 0
	v_mfma_f32_16x16x32_bf16 v[72:75], v[138:141], v[170:173], 0
	v_mfma_f32_16x16x32_bf16 v[126:129], v[134:137], v[150:153], v[126:129]
	v_mfma_f32_16x16x32_bf16 v[122:125], v[142:145], v[150:153], v[122:125]
	v_mfma_f32_16x16x32_bf16 v[110:113], v[134:137], v[158:161], v[110:113]
	v_mfma_f32_16x16x32_bf16 v[106:109], v[142:145], v[158:161], v[106:109]
	v_mfma_f32_16x16x32_bf16 v[92:95], v[134:137], v[166:169], v[92:95]
	v_mfma_f32_16x16x32_bf16 v[88:91], v[142:145], v[166:169], v[88:91]
	v_mfma_f32_16x16x32_bf16 v[76:79], v[134:137], v[174:177], v[76:79]
	v_mfma_f32_16x16x32_bf16 v[72:75], v[142:145], v[174:177], v[72:75]
	s_setprio 0
	s_barrier
	s_add_i32 s43, 0, 0x14000
	s_add_i32 s0, s42, s5
	v_add_u32_e32 v196, s43, v198
	v_lshl_add_u64 v[206:207], s[20:21], 0, v[96:97]
	s_mov_b32 m0, s0
	ds_read_b128 v[184:187], v196
	ds_read_b128 v[188:191], v196 offset:1024
	ds_read_b128 v[192:195], v196 offset:2048
	ds_read_b128 v[202:205], v196 offset:3072
	global_load_lds_dwordx4 v[206:207], off
	v_lshl_add_u64 v[208:209], s[20:21], 0, v[178:179]
	s_add_i32 m0, s0, 0x2000
	s_nop 0
	global_load_lds_dwordx4 v[208:209], off
	s_barrier
; #define PG8_STAGE(bufoff, gbase, voff) do { _Pragma("unroll") for (int _i = 0; _i < 2; ++_i) \
;         __builtin_amdgcn_global_load_lds((const unsigned*)((const char*)(gbase) + (voff)[_i]), (LAS unsigned*)(lds + (bufoff) + ldsw + _i * 8192), 16, 0, 0); } while (0)
; #define PG8_LDA(dst, b, h) do { _Pragma("unroll") for (int m = 0; m < 4; ++m) _Pragma("unroll") for (int k = 0; k < 2; ++k) dst[m][k] = *(const LAS bf16x8*)(lds + PG8_SA(b, h) + aoff + m * 2048 + k * 1024); } while (0)
; #define PG8_LDB(dst, b, h) do { _Pragma("unroll") for (int n = 0; n < 2; ++n) _Pragma("unroll") for (int k = 0; k < 2; ++k) dst[n][k] = *(const LAS bf16x8*)(lds + PG8_SB(b, h) + boff + n * 2048 + k * 1024); } while (0)
; #define PG8_MMA(ai, bj, At, Bt) do { __builtin_amdgcn_s_setprio(1); _Pragma("unroll") for (int m = 0; m < 4; ++m) _Pragma("unroll") for (int n = 0; n < 2; ++n) _Pragma("unroll") for (int k = 0; k < 2; ++k) \
;         acc[ai][bj][m][n] = __builtin_amdgcn_mfma_f32_16x16x32_bf16(Bt[n][k], At[m][k], acc[ai][bj][m][n], 0, 0, 0); __builtin_amdgcn_s_setprio(0); } while (0)
; #define PG8_WAIT_V(n) asm volatile("s_waitcnt vmcnt(" #n ")" ::: "memory")
; #define PG8_WAIT_L(n) asm volatile("s_waitcnt lgkmcnt(" #n ")" ::: "memory")
; #define PG8_BAR __builtin_amdgcn_s_barrier()
; #define PG8_SCHED __builtin_amdgcn_sched_barrier(0)
; template <class Epi, class Sched>
; DI void gemm_phase(LAS unsigned char* lds, const Gemm g, const Sched& S, const Epi& E) {
;     ...
;             PG8_LDB(B1, 0, 1); PG8_STAGE(PG8_SB(0, 0), b2, voffB);
;             PG8_BAR; PG8_WAIT_L(0); PG8_MMA(0, 1, At, B1); PG8_BAR;
;             PG8_LDA(At, 0, 1); PG8_STAGE(PG8_SA(0, 0), a2, voffA);
;             PG8_BAR; PG8_WAIT_L(0); PG8_MMA(1, 0, At, B0); PG8_BAR; PG8_SCHED;
;             PG8_STAGE(PG8_SB(0, 1), b2 + hstep, voffB);
;             PG8_WAIT_V(6); PG8_BAR; PG8_MMA(1, 1, At, B1); PG8_BAR;
	s_waitcnt lgkmcnt(0)
	s_setprio 1
	s_waitcnt lgkmcnt(0)
	v_mfma_f32_16x16x32_bf16 v[118:121], v[184:187], v[146:149], 0
	v_mfma_f32_16x16x32_bf16 v[114:117], v[192:195], v[146:149], 0
	v_mfma_f32_16x16x32_bf16 v[102:105], v[184:187], v[154:157], 0
	v_mfma_f32_16x16x32_bf16 v[98:101], v[192:195], v[154:157], 0
	v_mfma_f32_16x16x32_bf16 v[84:87], v[184:187], v[162:165], 0
	v_mfma_f32_16x16x32_bf16 v[80:83], v[192:195], v[162:165], 0
	v_mfma_f32_16x16x32_bf16 v[68:71], v[184:187], v[170:173], 0
	v_mfma_f32_16x16x32_bf16 v[64:67], v[192:195], v[170:173], 0
	v_mfma_f32_16x16x32_bf16 v[118:121], v[188:191], v[150:153], v[118:121]
	v_mfma_f32_16x16x32_bf16 v[114:117], v[202:205], v[150:153], v[114:117]
	v_mfma_f32_16x16x32_bf16 v[102:105], v[188:191], v[158:161], v[102:105]
	v_mfma_f32_16x16x32_bf16 v[98:101], v[202:205], v[158:161], v[98:101]
	v_mfma_f32_16x16x32_bf16 v[84:87], v[188:191], v[166:169], v[84:87]
	v_mfma_f32_16x16x32_bf16 v[80:83], v[202:205], v[166:169], v[80:83]
	v_mfma_f32_16x16x32_bf16 v[68:71], v[188:191], v[174:177], v[68:71]
	v_mfma_f32_16x16x32_bf16 v[64:67], v[202:205], v[174:177], v[64:67]
	s_setprio 0
	s_mov_b32 m0, s6
	v_lshl_add_u64 v[210:211], s[22:23], 0, v[96:97]
	s_barrier
	ds_read_b128 v[146:149], v200 offset:16384
	ds_read_b128 v[150:153], v200 offset:17408
	ds_read_b128 v[154:157], v200 offset:18432
	ds_read_b128 v[158:161], v200 offset:19456
	ds_read_b128 v[162:165], v200 offset:20480
	ds_read_b128 v[166:169], v200 offset:21504
	ds_read_b128 v[170:173], v200 offset:22528
	ds_read_b128 v[174:177], v200 offset:23552
	global_load_lds_dwordx4 v[210:211], off
	v_lshl_add_u64 v[212:213], s[22:23], 0, v[178:179]
	s_mov_b32 m0, s7
	s_nop 0
	global_load_lds_dwordx4 v[212:213], off
	s_barrier
	s_waitcnt lgkmcnt(0)
	s_setprio 1
	s_waitcnt lgkmcnt(0)
	v_mfma_f32_16x16x32_bf16 v[60:63], v[130:133], v[146:149], 0
	v_mfma_f32_16x16x32_bf16 v[56:59], v[138:141], v[146:149], 0
	v_mfma_f32_16x16x32_bf16 v[44:47], v[130:133], v[154:157], 0
	v_mfma_f32_16x16x32_bf16 v[40:43], v[138:141], v[154:157], 0
	v_mfma_f32_16x16x32_bf16 v[28:31], v[130:133], v[162:165], 0
	v_mfma_f32_16x16x32_bf16 v[24:27], v[138:141], v[162:165], 0
	v_mfma_f32_16x16x32_bf16 v[12:15], v[130:133], v[170:173], 0
	v_mfma_f32_16x16x32_bf16 v[8:11], v[138:141], v[170:173], 0
	v_mfma_f32_16x16x32_bf16 v[60:63], v[134:137], v[150:153], v[60:63]
	v_mfma_f32_16x16x32_bf16 v[56:59], v[142:145], v[150:153], v[56:59]
	v_mfma_f32_16x16x32_bf16 v[44:47], v[134:137], v[158:161], v[44:47]
	v_mfma_f32_16x16x32_bf16 v[40:43], v[142:145], v[158:161], v[40:43]
	v_mfma_f32_16x16x32_bf16 v[28:31], v[134:137], v[166:169], v[28:31]
	v_mfma_f32_16x16x32_bf16 v[24:27], v[142:145], v[166:169], v[24:27]
	v_mfma_f32_16x16x32_bf16 v[12:15], v[134:137], v[174:177], v[12:15]
	v_mfma_f32_16x16x32_bf16 v[8:11], v[142:145], v[174:177], v[8:11]
	s_setprio 0
	s_barrier
	s_add_u32 s0, s20, 0x40000
	s_addc_u32 s1, s21, 0
	s_add_i32 s42, s43, s5
	v_lshl_add_u64 v[130:131], s[0:1], 0, v[96:97]
	s_mov_b32 m0, s42
	s_nop 0
	global_load_lds_dwordx4 v[130:131], off
	v_lshl_add_u64 v[130:131], s[0:1], 0, v[178:179]
	s_add_i32 m0, s42, 0x2000
	s_nop 0
	global_load_lds_dwordx4 v[130:131], off
	s_waitcnt vmcnt(6)
	s_barrier
	s_setprio 1
	v_mfma_f32_16x16x32_bf16 v[52:55], v[184:187], v[146:149], 0
	v_mfma_f32_16x16x32_bf16 v[48:51], v[192:195], v[146:149], 0
	v_mfma_f32_16x16x32_bf16 v[36:39], v[184:187], v[154:157], 0
	v_mfma_f32_16x16x32_bf16 v[32:35], v[192:195], v[154:157], 0
	v_mfma_f32_16x16x32_bf16 v[20:23], v[184:187], v[162:165], 0
	v_mfma_f32_16x16x32_bf16 v[16:19], v[192:195], v[162:165], 0
	v_mfma_f32_16x16x32_bf16 v[4:7], v[184:187], v[170:173], 0
	v_mfma_f32_16x16x32_bf16 v[0:3], v[192:195], v[170:173], 0
	v_mfma_f32_16x16x32_bf16 v[52:55], v[188:191], v[150:153], v[52:55]
	v_mfma_f32_16x16x32_bf16 v[48:51], v[202:205], v[150:153], v[48:51]
	v_mfma_f32_16x16x32_bf16 v[36:39], v[188:191], v[158:161], v[36:39]
	v_mfma_f32_16x16x32_bf16 v[32:35], v[202:205], v[158:161], v[32:35]
	v_mfma_f32_16x16x32_bf16 v[20:23], v[188:191], v[166:169], v[20:23]
	v_mfma_f32_16x16x32_bf16 v[16:19], v[202:205], v[166:169], v[16:19]
	v_mfma_f32_16x16x32_bf16 v[4:7], v[188:191], v[174:177], v[4:7]
	v_mfma_f32_16x16x32_bf16 v[0:3], v[202:205], v[174:177], v[0:3]
	s_setprio 0
	s_branch .Lkmid_22849

; #define PG8_STAGE(bufoff, gbase, voff) do { _Pragma("unroll") for (int _i = 0; _i < 2; ++_i) \
;         __builtin_amdgcn_global_load_lds((const unsigned*)((const char*)(gbase) + (voff)[_i]), (LAS unsigned*)(lds + (bufoff) + ldsw + _i * 8192), 16, 0, 0); } while (0)
; #define PG8_LDA(dst, b, h) do { _Pragma("unroll") for (int m = 0; m < 4; ++m) _Pragma("unroll") for (int k = 0; k < 2; ++k) dst[m][k] = *(const LAS bf16x8*)(lds + PG8_SA(b, h) + aoff + m * 2048 + k * 1024); } while (0)
; #define PG8_LDB(dst, b, h) do { _Pragma("unroll") for (int n = 0; n < 2; ++n) _Pragma("unroll") for (int k = 0; k < 2; ++k) dst[n][k] = *(const LAS bf16x8*)(lds + PG8_SB(b, h) + boff + n * 2048 + k * 1024); } while (0)
; #define PG8_MMA(ai, bj, At, Bt) do { __builtin_amdgcn_s_setprio(1); _Pragma("unroll") for (int m = 0; m < 4; ++m) _Pragma("unroll") for (int n = 0; n < 2; ++n) _Pragma("unroll") for (int k = 0; k < 2; ++k) \
;         acc[ai][bj][m][n] = __builtin_amdgcn_mfma_f32_16x16x32_bf16(Bt[n][k], At[m][k], acc[ai][bj][m][n], 0, 0, 0); __builtin_amdgcn_s_setprio(0); } while (0)
; #define PG8_WAIT_L(n) asm volatile("s_waitcnt lgkmcnt(" #n ")" ::: "memory")
; #define PG8_BAR __builtin_amdgcn_s_barrier()
; #define PG8_SCHED __builtin_amdgcn_sched_barrier(0)
; template <class Epi, class Sched>
; DI void gemm_phase(LAS unsigned char* lds, const Gemm g, const Sched& S, const Epi& E) {
;     ...
;             PG8_LDB(B0, 1, 0); PG8_SCHED; PG8_LDA(At, 1, 0); PG8_STAGE(PG8_SA(0, 1), a2 + hstep, voffA);
;             PG8_WAIT_L(8); PG8_BAR; PG8_WAIT_L(0); PG8_MMA(0, 0, At, B0); PG8_BAR; PG8_SCHED;
;             PG8_LDB(B1, 1, 1); PG8_STAGE(PG8_SB(1, 0), b3, voffB);
;             PG8_BAR; PG8_WAIT_L(0); PG8_MMA(0, 1, At, B1); PG8_BAR;
;             PG8_LDA(At, 1, 1); PG8_STAGE(PG8_SA(1, 0), a3, voffA);
;             PG8_BAR; PG8_WAIT_L(0); PG8_MMA(1, 0, At, B0); PG8_BAR; PG8_SCHED;
.Lkmid_22849:
	s_add_i32 s42, 0, 0x18000
	v_add_u32_e32 v142, s42, v198
	s_barrier
	ds_read_b128 v[130:133], v142
	ds_read_b128 v[134:137], v142 offset:1024
	ds_read_b128 v[138:141], v142 offset:2048
	ds_read_b128 v[142:145], v142 offset:3072
	s_add_u32 s0, s22, 0x40000
	s_addc_u32 s1, s23, 0
	s_mov_b32 m0, s24
	v_lshl_add_u64 v[184:185], s[0:1], 0, v[96:97]
	ds_read_b128 v[146:149], v200 offset:32768
	ds_read_b128 v[150:153], v200 offset:33792
	ds_read_b128 v[154:157], v200 offset:34816
	ds_read_b128 v[158:161], v200 offset:35840
	ds_read_b128 v[162:165], v200 offset:36864
	ds_read_b128 v[166:169], v200 offset:37888
	ds_read_b128 v[170:173], v200 offset:38912
	ds_read_b128 v[174:177], v200 offset:39936
	global_load_lds_dwordx4 v[184:185], off
	v_lshl_add_u64 v[184:185], s[0:1], 0, v[178:179]
	s_mov_b32 m0, s25
	s_nop 0
	global_load_lds_dwordx4 v[184:185], off
	s_waitcnt lgkmcnt(8)
	s_barrier
	s_waitcnt lgkmcnt(0)
	s_setprio 1
	s_waitcnt lgkmcnt(0)
	v_mfma_f32_16x16x32_bf16 v[126:129], v[130:133], v[146:149], v[126:129]
	v_mfma_f32_16x16x32_bf16 v[122:125], v[138:141], v[146:149], v[122:125]
	v_mfma_f32_16x16x32_bf16 v[110:113], v[130:133], v[154:157], v[110:113]
	v_mfma_f32_16x16x32_bf16 v[106:109], v[138:141], v[154:157], v[106:109]
	v_mfma_f32_16x16x32_bf16 v[92:95], v[130:133], v[162:165], v[92:95]
	v_mfma_f32_16x16x32_bf16 v[88:91], v[138:141], v[162:165], v[88:91]
	v_mfma_f32_16x16x32_bf16 v[76:79], v[130:133], v[170:173], v[76:79]
	v_mfma_f32_16x16x32_bf16 v[72:75], v[138:141], v[170:173], v[72:75]
	v_mfma_f32_16x16x32_bf16 v[126:129], v[134:137], v[150:153], v[126:129]
	v_mfma_f32_16x16x32_bf16 v[122:125], v[142:145], v[150:153], v[122:125]
	v_mfma_f32_16x16x32_bf16 v[110:113], v[134:137], v[158:161], v[110:113]
	v_mfma_f32_16x16x32_bf16 v[106:109], v[142:145], v[158:161], v[106:109]
	v_mfma_f32_16x16x32_bf16 v[92:95], v[134:137], v[166:169], v[92:95]
	v_mfma_f32_16x16x32_bf16 v[88:91], v[142:145], v[166:169], v[88:91]
	v_mfma_f32_16x16x32_bf16 v[76:79], v[134:137], v[174:177], v[76:79]
	v_mfma_f32_16x16x32_bf16 v[72:75], v[142:145], v[174:177], v[72:75]
	s_setprio 0
	s_barrier
	s_add_i32 s22, 0, 0x1c000
	s_add_i32 s0, s42, s5
	v_add_u32_e32 v196, s22, v198
	v_lshl_add_u64 v[206:207], v[206:207], 0, s[36:37]
	s_mov_b32 m0, s0
	ds_read_b128 v[184:187], v196
	ds_read_b128 v[188:191], v196 offset:1024
	ds_read_b128 v[192:195], v196 offset:2048
	ds_read_b128 v[202:205], v196 offset:3072
	global_load_lds_dwordx4 v[206:207], off
	v_lshl_add_u64 v[206:207], v[208:209], 0, s[36:37]
	s_add_i32 m0, s0, 0x2000
	s_nop 0
	global_load_lds_dwordx4 v[206:207], off
	s_barrier
	s_waitcnt lgkmcnt(0)
	s_setprio 1
	s_waitcnt lgkmcnt(0)
	v_mfma_f32_16x16x32_bf16 v[118:121], v[184:187], v[146:149], v[118:121]
	v_mfma_f32_16x16x32_bf16 v[114:117], v[192:195], v[146:149], v[114:117]
	v_mfma_f32_16x16x32_bf16 v[102:105], v[184:187], v[154:157], v[102:105]
	v_mfma_f32_16x16x32_bf16 v[98:101], v[192:195], v[154:157], v[98:101]
	v_mfma_f32_16x16x32_bf16 v[84:87], v[184:187], v[162:165], v[84:87]
	v_mfma_f32_16x16x32_bf16 v[80:83], v[192:195], v[162:165], v[80:83]
	v_mfma_f32_16x16x32_bf16 v[68:71], v[184:187], v[170:173], v[68:71]
	v_mfma_f32_16x16x32_bf16 v[64:67], v[192:195], v[170:173], v[64:67]
	v_mfma_f32_16x16x32_bf16 v[118:121], v[188:191], v[150:153], v[118:121]
	v_mfma_f32_16x16x32_bf16 v[114:117], v[202:205], v[150:153], v[114:117]
	v_mfma_f32_16x16x32_bf16 v[102:105], v[188:191], v[158:161], v[102:105]
	v_mfma_f32_16x16x32_bf16 v[98:101], v[202:205], v[158:161], v[98:101]
	v_mfma_f32_16x16x32_bf16 v[84:87], v[188:191], v[166:169], v[84:87]
	v_mfma_f32_16x16x32_bf16 v[80:83], v[202:205], v[166:169], v[80:83]
	v_mfma_f32_16x16x32_bf16 v[68:71], v[188:191], v[174:177], v[68:71]
	v_mfma_f32_16x16x32_bf16 v[64:67], v[202:205], v[174:177], v[64:67]
	s_setprio 0
	s_mov_b32 m0, s27
	v_lshl_add_u64 v[206:207], v[210:211], 0, s[36:37]
	s_barrier
	ds_read_b128 v[146:149], v200 offset:49152
	ds_read_b128 v[150:153], v200 offset:50176
	ds_read_b128 v[154:157], v200 offset:51200
	ds_read_b128 v[158:161], v200 offset:52224
	ds_read_b128 v[162:165], v200 offset:53248
	ds_read_b128 v[166:169], v200 offset:54272
	ds_read_b128 v[170:173], v200 offset:55296
	ds_read_b128 v[174:177], v200 offset:56320
	global_load_lds_dwordx4 v[206:207], off
	v_lshl_add_u64 v[206:207], v[212:213], 0, s[36:37]
	s_mov_b32 m0, s28
	s_nop 0
	global_load_lds_dwordx4 v[206:207], off
	s_barrier
	s_waitcnt lgkmcnt(0)
	s_setprio 1
	s_waitcnt lgkmcnt(0)
	v_mfma_f32_16x16x32_bf16 v[60:63], v[130:133], v[146:149], v[60:63]
	v_mfma_f32_16x16x32_bf16 v[56:59], v[138:141], v[146:149], v[56:59]
	v_mfma_f32_16x16x32_bf16 v[44:47], v[130:133], v[154:157], v[44:47]
	v_mfma_f32_16x16x32_bf16 v[40:43], v[138:141], v[154:157], v[40:43]
	v_mfma_f32_16x16x32_bf16 v[28:31], v[130:133], v[162:165], v[28:31]
	v_mfma_f32_16x16x32_bf16 v[24:27], v[138:141], v[162:165], v[24:27]
	v_mfma_f32_16x16x32_bf16 v[12:15], v[130:133], v[170:173], v[12:15]
	v_mfma_f32_16x16x32_bf16 v[8:11], v[138:141], v[170:173], v[8:11]
	v_mfma_f32_16x16x32_bf16 v[60:63], v[134:137], v[150:153], v[60:63]
	v_mfma_f32_16x16x32_bf16 v[56:59], v[142:145], v[150:153], v[56:59]
	v_mfma_f32_16x16x32_bf16 v[44:47], v[134:137], v[158:161], v[44:47]
	v_mfma_f32_16x16x32_bf16 v[40:43], v[142:145], v[158:161], v[40:43]
	v_mfma_f32_16x16x32_bf16 v[28:31], v[134:137], v[166:169], v[28:31]
	v_mfma_f32_16x16x32_bf16 v[24:27], v[142:145], v[166:169], v[24:27]
	v_mfma_f32_16x16x32_bf16 v[12:15], v[134:137], v[174:177], v[12:15]
	v_mfma_f32_16x16x32_bf16 v[8:11], v[142:145], v[174:177], v[8:11]
	s_setprio 0
	s_barrier
; #define PG8_STAGE(bufoff, gbase, voff) do { _Pragma("unroll") for (int _i = 0; _i < 2; ++_i) \
;         __builtin_amdgcn_global_load_lds((const unsigned*)((const char*)(gbase) + (voff)[_i]), (LAS unsigned*)(lds + (bufoff) + ldsw + _i * 8192), 16, 0, 0); } while (0)
; #define PG8_MMA(ai, bj, At, Bt) do { __builtin_amdgcn_s_setprio(1); _Pragma("unroll") for (int m = 0; m < 4; ++m) _Pragma("unroll") for (int n = 0; n < 2; ++n) _Pragma("unroll") for (int k = 0; k < 2; ++k) \
;         acc[ai][bj][m][n] = __builtin_amdgcn_mfma_f32_16x16x32_bf16(Bt[n][k], At[m][k], acc[ai][bj][m][n], 0, 0, 0); __builtin_amdgcn_s_setprio(0); } while (0)
; #define PG8_WAIT_V(n) asm volatile("s_waitcnt vmcnt(" #n ")" ::: "memory")
; #define PG8_BAR __builtin_amdgcn_s_barrier()
; template <class Epi, class Sched>
; DI void gemm_phase(LAS unsigned char* lds, const Gemm g, const Sched& S, const Epi& E) {
;     ...
;             PG8_STAGE(PG8_SB(1, 1), b3 + hstep, voffB);
;             PG8_WAIT_V(6); PG8_BAR; PG8_MMA(1, 1, At, B1); PG8_BAR;
	s_add_u32 s0, s20, 0x40080
	s_addc_u32 s1, s21, 0
	s_add_i32 s20, s22, s5
	v_lshl_add_u64 v[130:131], s[0:1], 0, v[96:97]
	s_mov_b32 m0, s20
	s_nop 0
	global_load_lds_dwordx4 v[130:131], off
	v_lshl_add_u64 v[130:131], s[0:1], 0, v[178:179]
	s_add_i32 m0, s20, 0x2000
	s_nop 0
	global_load_lds_dwordx4 v[130:131], off
	s_waitcnt vmcnt(6)
	s_barrier
	s_setprio 1
	v_mfma_f32_16x16x32_bf16 v[52:55], v[184:187], v[146:149], v[52:55]
	v_mfma_f32_16x16x32_bf16 v[48:51], v[192:195], v[146:149], v[48:51]
	v_mfma_f32_16x16x32_bf16 v[36:39], v[184:187], v[154:157], v[36:39]
	v_mfma_f32_16x16x32_bf16 v[32:35], v[192:195], v[154:157], v[32:35]
	v_mfma_f32_16x16x32_bf16 v[20:23], v[184:187], v[162:165], v[20:23]
	v_mfma_f32_16x16x32_bf16 v[16:19], v[192:195], v[162:165], v[16:19]
	v_mfma_f32_16x16x32_bf16 v[4:7], v[184:187], v[170:173], v[4:7]
	v_mfma_f32_16x16x32_bf16 v[0:3], v[192:195], v[170:173], v[0:3]
	v_mfma_f32_16x16x32_bf16 v[52:55], v[188:191], v[150:153], v[52:55]
	v_mfma_f32_16x16x32_bf16 v[48:51], v[202:205], v[150:153], v[48:51]
	v_mfma_f32_16x16x32_bf16 v[36:39], v[188:191], v[158:161], v[36:39]
	v_mfma_f32_16x16x32_bf16 v[32:35], v[202:205], v[158:161], v[32:35]
	v_mfma_f32_16x16x32_bf16 v[20:23], v[188:191], v[166:169], v[20:23]
	v_mfma_f32_16x16x32_bf16 v[16:19], v[202:205], v[166:169], v[16:19]
	v_mfma_f32_16x16x32_bf16 v[4:7], v[188:191], v[174:177], v[4:7]
	v_mfma_f32_16x16x32_bf16 v[0:3], v[202:205], v[174:177], v[0:3]
	s_setprio 0
	s_add_i32 s41, s41, 2
	s_add_u32 s18, s18, 0x100
	s_addc_u32 s19, s19, 0
	s_add_u32 s34, s34, 0x100
	s_addc_u32 s40, s40, 0
	s_cmp_lt_u32 s41, 14
	s_barrier
	s_cbranch_scc1 .LBB0_1684
; #define LAS __attribute__((address_space(3)))
; DI unsigned pk2(float lo, float hi) { f32x2 v = {lo, hi}; hbf2 r = __builtin_convertvector(v, hbf2); return __builtin_bit_cast(unsigned, r); }
;     DI void operator()(f32x4 (&acc)[2][2][4][2], const Unit& u, int wr, int wc, int fr, int fq, LAS unsigned char* lds) const {
;         const int row0 = u.pm * 256 + wr * 64 + fr, col0 = u.pn * 256 + wc * 32 + 4 * fq;
; #pragma unroll
;         for (int ai = 0; ai < 2; ++ai) {
;             f32x4 xv[4][2][2];
; #pragma unroll
;             for (int m = 0; m < 4; ++m) {
;                 const int row = row0 + ai * 128 + m * 16;
;                 const float* xi = (row < TP ? xin_p + (size_t)row * DM : xin_s + (size_t)(row - TP) * DM) + col0;
; #pragma unroll
;                 for (int bj = 0; bj < 2; ++bj)
; #pragma unroll
;                     for (int n = 0; n < 2; ++n) xv[m][bj][n] = *(const f32x4*)(xi + bj * 128 + n * 16);
;             }
; #pragma unroll
;             for (int m = 0; m < 4; ++m) {
;                 const int row = row0 + ai * 128 + m * 16;
;                 float* xo = X + (size_t)row * DM + col0; bf16_t* xb = XB + (size_t)row * DM + col0;
;                 float ssq = 0.f;
; #pragma unroll
;                 for (int bj = 0; bj < 2; ++bj)
; #pragma unroll
;                     for (int n = 0; n < 2; ++n) {
;                         const int c = bj * 128 + n * 16;
;                         const f32x4 o = xv[m][bj][n] + acc[ai][bj][m][n] * scale;
;                         *(f32x4*)(xo + c) = o;
;                         if (wxb) { u32x2 w; w.x = pk2(o[0], o[1]); w.y = pk2(o[2], o[3]); *(u32x2*)(xb + c) = w; }
;                         ssq += (o[0] * o[0] + o[1] * o[1]) + (o[2] * o[2] + o[3] * o[3]);
;                     }
;                 ssq += __shfl_xor(ssq, 16); ssq += __shfl_xor(ssq, 32);
;                 if (fq == 0) SS[(size_t)row * 16 + u.pn * 4 + wc] = ssq;
;             }
	v_lshl_add_u32 v186, s2, 8, v197
	v_add_u32_e32 v130, 0xffff8000, v186
	v_ashrrev_i32_e32 v187, 31, v186
	v_cmp_gt_i32_e32 vcc, s86, v186
	v_lshl_or_b32 v184, s30, 8, v199
	v_mov_b32_e32 v134, s63
	v_cndmask_b32_e32 v131, 0, v187, vcc
	v_cndmask_b32_e32 v130, v130, v186, vcc
	v_mov_b32_e32 v135, s91
	v_mov_b32_e32 v136, s62
	v_mov_b32_e32 v137, s90
	v_ashrrev_i32_e32 v185, 31, v184
	v_cndmask_b32_e32 v133, v134, v135, vcc
	v_cndmask_b32_e32 v132, v136, v137, vcc
	v_lshlrev_b64 v[130:131], 12, v[130:131]
	v_lshl_add_u64 v[130:131], v[132:133], 0, v[130:131]
	v_lshlrev_b64 v[188:189], 2, v[184:185]
	v_lshl_add_u64 v[130:131], v[130:131], 0, v[188:189]
	global_load_dwordx4 v[204:207], v[130:131], off
	global_load_dwordx4 v[208:211], v[130:131], off offset:64
	global_load_dwordx4 v[212:215], v[130:131], off offset:512
	global_load_dwordx4 v[216:219], v[130:131], off offset:576
	v_or_b32_e32 v194, 16, v186
	v_ashrrev_i32_e32 v195, 31, v194
	v_add_u32_e32 v130, 0xffff8010, v186
	v_cmp_gt_i32_e32 vcc, s86, v194
	v_or_b32_e32 v192, 32, v186
	v_ashrrev_i32_e32 v193, 31, v192
	v_cndmask_b32_e32 v131, 0, v195, vcc
	v_cndmask_b32_e32 v130, v130, v194, vcc
	v_cndmask_b32_e32 v133, v134, v135, vcc
	v_cndmask_b32_e32 v132, v136, v137, vcc
	v_lshlrev_b64 v[130:131], 12, v[130:131]
	v_lshl_add_u64 v[130:131], v[132:133], 0, v[130:131]
	v_lshl_add_u64 v[130:131], v[130:131], 0, v[188:189]
	global_load_dwordx4 v[174:177], v[130:131], off
	global_load_dwordx4 v[170:173], v[130:131], off offset:64
	global_load_dwordx4 v[166:169], v[130:131], off offset:512
	global_load_dwordx4 v[162:165], v[130:131], off offset:576
	v_add_u32_e32 v130, 0xffff8020, v186
	v_cmp_gt_i32_e32 vcc, s86, v192
	v_or_b32_e32 v190, 48, v186
	v_ashrrev_i32_e32 v191, 31, v190
	v_cndmask_b32_e32 v131, 0, v193, vcc
	v_cndmask_b32_e32 v130, v130, v192, vcc
	v_cndmask_b32_e32 v133, v134, v135, vcc
	v_cndmask_b32_e32 v132, v136, v137, vcc
	v_lshlrev_b64 v[130:131], 12, v[130:131]
	v_lshl_add_u64 v[130:131], v[132:133], 0, v[130:131]
	v_lshl_add_u64 v[130:131], v[130:131], 0, v[188:189]
	global_load_dwordx4 v[158:161], v[130:131], off
	global_load_dwordx4 v[154:157], v[130:131], off offset:64
	global_load_dwordx4 v[150:153], v[130:131], off offset:512
	global_load_dwordx4 v[146:149], v[130:131], off offset:576
	v_add_u32_e32 v130, 0xffff8030, v186
	v_cmp_gt_i32_e32 vcc, s86, v190
	v_lshlrev_b64 v[220:221], 12, v[186:187]
	v_lshl_add_u64 v[220:221], s[90:91], 0, v[220:221]
	v_cndmask_b32_e32 v131, 0, v191, vcc
	v_cndmask_b32_e32 v130, v130, v190, vcc
	v_cndmask_b32_e32 v133, v134, v135, vcc
	v_cndmask_b32_e32 v132, v136, v137, vcc
	v_lshlrev_b64 v[130:131], 12, v[130:131]
	v_lshl_add_u64 v[130:131], v[132:133], 0, v[130:131]
	v_lshl_add_u64 v[130:131], v[130:131], 0, v[188:189]
	global_load_dwordx4 v[142:145], v[130:131], off
	global_load_dwordx4 v[138:141], v[130:131], off offset:64
	global_load_dwordx4 v[134:137], v[130:131], off offset:512
	s_nop 0
	global_load_dwordx4 v[130:133], v[130:131], off offset:576
	v_lshl_add_u64 v[220:221], v[220:221], 0, v[188:189]
	v_lshlrev_b64 v[222:223], 11, v[186:187]
	v_lshl_add_u64 v[222:223], s[72:73], 0, v[222:223]
	v_lshl_add_u64 v[222:223], v[184:185], 1, v[222:223]
	v_and_b32_e32 v201, 64, v229
	v_xor_b32_e32 v196, 16, v229
	v_add_u32_e32 v201, 64, v201
	v_cmp_lt_i32_e32 vcc, v196, v201
	v_xor_b32_e32 v202, 32, v229
	s_waitcnt vmcnt(0)
	v_pk_add_f32 v[128:129], v[128:129], v[206:207]
	v_pk_add_f32 v[126:127], v[126:127], v[204:205]
	global_store_dwordx4 v[220:221], v[126:129], off
	v_cvt_pk_bf16_f32 v204, v126, v127
	v_cvt_pk_bf16_f32 v205, v128, v129
	v_mul_f32_e32 v127, v127, v127
	v_fmac_f32_e32 v127, v126, v126
	v_mul_f32_e32 v126, v129, v129
	v_fmac_f32_e32 v126, v128, v128
	v_pk_add_f32 v[124:125], v[124:125], v[210:211]
	v_pk_add_f32 v[122:123], v[122:123], v[208:209]
	global_store_dwordx2 v[222:223], v[204:205], off
	v_add_f32_e32 v128, v127, v126
	global_store_dwordx4 v[220:221], v[122:125], off offset:64
	v_cvt_pk_bf16_f32 v126, v122, v123
	v_pk_add_f32 v[120:121], v[120:121], v[214:215]
	v_mul_f32_e32 v123, v123, v123
	v_fmac_f32_e32 v123, v122, v122
	v_mul_f32_e32 v122, v125, v125
	v_fmac_f32_e32 v122, v124, v124
	v_pk_add_f32 v[118:119], v[118:119], v[212:213]
	v_cvt_pk_bf16_f32 v127, v124, v125
	v_add_f32_e32 v122, v123, v122
	v_mul_f32_e32 v123, v119, v119
	v_mul_f32_e32 v124, v121, v121
	v_fmac_f32_e32 v123, v118, v118
	v_fmac_f32_e32 v124, v120, v120
	v_add_f32_e32 v122, v128, v122
	v_add_f32_e32 v123, v123, v124
	global_store_dwordx2 v[222:223], v[126:127], off offset:32
	v_add_f32_e32 v126, v122, v123
	v_pk_add_f32 v[124:125], v[116:117], v[218:219]
	v_pk_add_f32 v[122:123], v[114:115], v[216:217]
	v_mul_f32_e32 v115, v125, v125
	v_mul_f32_e32 v114, v123, v123
	v_fmac_f32_e32 v114, v122, v122
	v_fmac_f32_e32 v115, v124, v124
	v_cndmask_b32_e32 v196, v229, v196, vcc
	v_add_f32_e32 v114, v114, v115
	v_lshlrev_b32_e32 v196, 2, v196
	v_add_f32_e32 v116, v126, v114
	ds_bpermute_b32 v117, v196, v116
	v_cmp_lt_i32_e32 vcc, v202, v201
	v_cvt_pk_bf16_f32 v114, v118, v119
	v_cvt_pk_bf16_f32 v115, v120, v121
	v_cndmask_b32_e32 v202, v229, v202, vcc
	v_lshlrev_b32_e32 v202, 2, v202
	global_store_dwordx4 v[220:221], v[118:121], off offset:512
	global_store_dwordx2 v[222:223], v[114:115], off offset:256
	s_waitcnt lgkmcnt(0)
	v_add_f32_e32 v114, v116, v117
	ds_bpermute_b32 v115, v202, v114
	v_cvt_pk_bf16_f32 v116, v122, v123
	v_cvt_pk_bf16_f32 v117, v124, v125
	global_store_dwordx4 v[220:221], v[122:125], off offset:576
	global_store_dwordx2 v[222:223], v[116:117], off offset:288
	s_and_saveexec_b64 s[18:19], s[38:39]
	s_cbranch_execz .LBB0_1687
	s_waitcnt lgkmcnt(0)
	v_add_f32_e32 v116, v114, v115
	s_lshl_b32 s0, s30, 2
	v_lshlrev_b64 v[114:115], 6, v[186:187]
	s_ashr_i32 s1, s0, 31
	v_lshl_add_u64 v[114:115], s[70:71], 0, v[114:115]
	v_lshl_add_u64 v[114:115], s[0:1], 2, v[114:115]
	s_lshl_b32 s68, s26, 2
	v_lshl_add_u64 v[114:115], v[114:115], 0, s[68:69]
	global_store_dword v[114:115], v116, off

; #define PG8_STAGE(bufoff, gbase, voff) do { _Pragma("unroll") for (int _i = 0; _i < 2; ++_i) \
;         __builtin_amdgcn_global_load_lds((const unsigned*)((const char*)(gbase) + (voff)[_i]), (LAS unsigned*)(lds + (bufoff) + ldsw + _i * 8192), 16, 0, 0); } while (0)
; #define PG8_LDA(dst, b, h) do { _Pragma("unroll") for (int m = 0; m < 4; ++m) _Pragma("unroll") for (int k = 0; k < 2; ++k) dst[m][k] = *(const LAS bf16x8*)(lds + PG8_SA(b, h) + aoff + m * 2048 + k * 1024); } while (0)
; #define PG8_LDB(dst, b, h) do { _Pragma("unroll") for (int n = 0; n < 2; ++n) _Pragma("unroll") for (int k = 0; k < 2; ++k) dst[n][k] = *(const LAS bf16x8*)(lds + PG8_SB(b, h) + boff + n * 2048 + k * 1024); } while (0)
; #define PG8_MMA(ai, bj, At, Bt) do { __builtin_amdgcn_s_setprio(1); _Pragma("unroll") for (int m = 0; m < 4; ++m) _Pragma("unroll") for (int n = 0; n < 2; ++n) _Pragma("unroll") for (int k = 0; k < 2; ++k) \
;         acc[ai][bj][m][n] = __builtin_amdgcn_mfma_f32_16x16x32_bf16(Bt[n][k], At[m][k], acc[ai][bj][m][n], 0, 0, 0); __builtin_amdgcn_s_setprio(0); } while (0)
; #define PG8_WAIT_L(n) asm volatile("s_waitcnt lgkmcnt(" #n ")" ::: "memory")
; template <class Epi, class Sched>
; DI void gemm_phase(LAS unsigned char* lds, const Gemm g, const Sched& S, const Epi& E) {
;     ...
;         const char* nA = has_next ? (const char*)g.A + (size_t)nxt.pm * tstep + (size_t)nxt.kt0 * kstep : cA; const char* nB = has_next ? (const char*)g.Bt + (size_t)nxt.pn * tstep + (size_t)nxt.kt0 * kstep : cB;
;         const int nt = cur.nkt;
;         for (int t = 0; t < nt; t += 2) {
;             const bool last = (t == nt - 2);
;             const char* a1 = cA + (size_t)(t + 1) * kstep;
;             const char* a2 = last ? nA : cA + (size_t)(t + 2) * kstep; const char* b2 = last ? nB : cB + (size_t)(t + 2) * kstep;
;             const char* a3 = a2 + kstep; const char* b3 = b2 + kstep;
;             PG8_LDB(B0, 0, 0); PG8_SCHED; PG8_LDA(At, 0, 0); PG8_STAGE(PG8_SA(1, 1), a1 + hstep, voffA);
;             PG8_WAIT_L(8); PG8_BAR; PG8_WAIT_L(0); PG8_MMA(0, 0, At, B0); PG8_BAR; PG8_SCHED;
;             PG8_LDB(B1, 0, 1); PG8_STAGE(PG8_SB(0, 0), b2, voffB);
;             PG8_BAR; PG8_WAIT_L(0); PG8_MMA(0, 1, At, B1); PG8_BAR;
;             PG8_LDA(At, 0, 1); PG8_STAGE(PG8_SA(0, 0), a2, voffA);
;             PG8_BAR; PG8_WAIT_L(0); PG8_MMA(1, 0, At, B0); PG8_BAR; PG8_SCHED;
.LBB0_1839:
	s_ashr_i32 s15, s14, 31
	s_lshl_b64 s[0:1], s[14:15], 19
	s_add_u32 s18, s72, s0
	s_addc_u32 s19, s73, s1
	s_and_b64 s[0:1], s[16:17], exec
	s_cselect_b32 s15, s19, s23
	s_cselect_b32 s34, s18, s22
	s_ashr_i32 s13, s12, 31
	s_lshl_b64 s[0:1], s[12:13], 19
	s_add_u32 s20, s5, s0
	s_addc_u32 s21, s6, s1
	s_and_b64 s[0:1], s[16:17], exec
	s_cselect_b32 s13, s21, s25
	s_cselect_b32 s42, s20, s24
	s_add_u32 s22, s22, 0x40080
	s_addc_u32 s23, s23, 0
	s_add_u32 s43, s24, 0x100
	v_mov_b32_e32 v0, 0
	s_addc_u32 s44, s25, 0
	s_mov_b32 s45, -2
	s_add_u32 s0, s22, 0xfffc0080
	s_addc_u32 s1, s23, -1
	s_add_i32 s46, 0, 0x10000
	v_add_u32_e32 v144, s46, v147
	ds_read_b128 v[140:143], v144
	ds_read_b128 v[152:155], v144 offset:1024
	ds_read_b128 v[156:159], v144 offset:2048
	ds_read_b128 v[160:163], v144 offset:3072
	s_cmp_eq_u32 s45, 12
	s_cselect_b32 s39, s15, s1
	s_cselect_b32 s38, s34, s0
	s_cselect_b32 s25, s13, s44
	s_cselect_b32 s24, s42, s43
	v_lshl_add_u64 v[144:145], s[22:23], 0, v[136:137]
	s_add_i32 m0, s26, 0xc000
	ds_read_b128 v[164:167], v150
	ds_read_b128 v[168:171], v150 offset:1024
	ds_read_b128 v[172:175], v150 offset:2048
	ds_read_b128 v[176:179], v150 offset:3072
	ds_read_b128 v[180:183], v150 offset:4096
	ds_read_b128 v[184:187], v150 offset:5120
	ds_read_b128 v[188:191], v150 offset:6144
	ds_read_b128 v[192:195], v150 offset:7168
	global_load_lds_dwordx4 v[144:145], off
	v_lshl_add_u64 v[144:145], s[22:23], 0, v[138:139]
	s_add_i32 m0, s26, 0xe000
	s_nop 0
	global_load_lds_dwordx4 v[144:145], off
	s_waitcnt lgkmcnt(8)
	s_barrier
	s_waitcnt lgkmcnt(0)
	s_setprio 1
	s_waitcnt lgkmcnt(0)
	v_mfma_f32_16x16x32_bf16 v[126:129], v[140:143], v[164:167], 0
	v_mfma_f32_16x16x32_bf16 v[122:125], v[156:159], v[164:167], 0
	v_mfma_f32_16x16x32_bf16 v[110:113], v[140:143], v[172:175], 0
	v_mfma_f32_16x16x32_bf16 v[106:109], v[156:159], v[172:175], 0
	v_mfma_f32_16x16x32_bf16 v[92:95], v[140:143], v[180:183], 0
	v_mfma_f32_16x16x32_bf16 v[88:91], v[156:159], v[180:183], 0
	v_mfma_f32_16x16x32_bf16 v[76:79], v[140:143], v[188:191], 0
	v_mfma_f32_16x16x32_bf16 v[72:75], v[156:159], v[188:191], 0
	v_mfma_f32_16x16x32_bf16 v[126:129], v[152:155], v[168:171], v[126:129]
	v_mfma_f32_16x16x32_bf16 v[122:125], v[160:163], v[168:171], v[122:125]
	v_mfma_f32_16x16x32_bf16 v[110:113], v[152:155], v[176:179], v[110:113]
	v_mfma_f32_16x16x32_bf16 v[106:109], v[160:163], v[176:179], v[106:109]
	v_mfma_f32_16x16x32_bf16 v[92:95], v[152:155], v[184:187], v[92:95]
	v_mfma_f32_16x16x32_bf16 v[88:91], v[160:163], v[184:187], v[88:91]
	v_mfma_f32_16x16x32_bf16 v[76:79], v[152:155], v[192:195], v[76:79]
	v_mfma_f32_16x16x32_bf16 v[72:75], v[160:163], v[192:195], v[72:75]
	s_setprio 0
	s_barrier
	s_add_i32 s47, 0, 0x14000
	v_add_u32_e32 v144, s47, v147
	s_add_i32 s0, s46, s7
	ds_read_b128 v[196:199], v144
	ds_read_b128 v[200:203], v144 offset:1024
	ds_read_b128 v[204:207], v144 offset:2048
	ds_read_b128 v[208:211], v144 offset:3072
	v_lshl_add_u64 v[144:145], s[24:25], 0, v[96:97]
	s_mov_b32 m0, s0
	v_lshl_add_u64 v[212:213], s[24:25], 0, v[134:135]
	global_load_lds_dwordx4 v[144:145], off
	s_add_i32 m0, s0, 0x2000
	s_nop 0
	global_load_lds_dwordx4 v[212:213], off
	s_barrier
; #define PG8_STAGE(bufoff, gbase, voff) do { _Pragma("unroll") for (int _i = 0; _i < 2; ++_i) \
;         __builtin_amdgcn_global_load_lds((const unsigned*)((const char*)(gbase) + (voff)[_i]), (LAS unsigned*)(lds + (bufoff) + ldsw + _i * 8192), 16, 0, 0); } while (0)
; #define PG8_LDA(dst, b, h) do { _Pragma("unroll") for (int m = 0; m < 4; ++m) _Pragma("unroll") for (int k = 0; k < 2; ++k) dst[m][k] = *(const LAS bf16x8*)(lds + PG8_SA(b, h) + aoff + m * 2048 + k * 1024); } while (0)
; #define PG8_LDB(dst, b, h) do { _Pragma("unroll") for (int n = 0; n < 2; ++n) _Pragma("unroll") for (int k = 0; k < 2; ++k) dst[n][k] = *(const LAS bf16x8*)(lds + PG8_SB(b, h) + boff + n * 2048 + k * 1024); } while (0)
; #define PG8_MMA(ai, bj, At, Bt) do { __builtin_amdgcn_s_setprio(1); _Pragma("unroll") for (int m = 0; m < 4; ++m) _Pragma("unroll") for (int n = 0; n < 2; ++n) _Pragma("unroll") for (int k = 0; k < 2; ++k) \
;         acc[ai][bj][m][n] = __builtin_amdgcn_mfma_f32_16x16x32_bf16(Bt[n][k], At[m][k], acc[ai][bj][m][n], 0, 0, 0); __builtin_amdgcn_s_setprio(0); } while (0)
; #define PG8_WAIT_V(n) asm volatile("s_waitcnt vmcnt(" #n ")" ::: "memory")
; #define PG8_WAIT_L(n) asm volatile("s_waitcnt lgkmcnt(" #n ")" ::: "memory")
; #define PG8_BAR __builtin_amdgcn_s_barrier()
; #define PG8_SCHED __builtin_amdgcn_sched_barrier(0)
; template <class Epi, class Sched>
; DI void gemm_phase(LAS unsigned char* lds, const Gemm g, const Sched& S, const Epi& E) {
;     ...
;             PG8_LDB(B1, 0, 1); PG8_STAGE(PG8_SB(0, 0), b2, voffB);
;             PG8_BAR; PG8_WAIT_L(0); PG8_MMA(0, 1, At, B1); PG8_BAR;
;             PG8_LDA(At, 0, 1); PG8_STAGE(PG8_SA(0, 0), a2, voffA);
;             PG8_BAR; PG8_WAIT_L(0); PG8_MMA(1, 0, At, B0); PG8_BAR; PG8_SCHED;
;             PG8_STAGE(PG8_SB(0, 1), b2 + hstep, voffB);
;             PG8_WAIT_V(6); PG8_BAR; PG8_MMA(1, 1, At, B1); PG8_BAR;
	s_waitcnt lgkmcnt(0)
	s_setprio 1
	s_waitcnt lgkmcnt(0)
	v_mfma_f32_16x16x32_bf16 v[118:121], v[196:199], v[164:167], 0
	v_mfma_f32_16x16x32_bf16 v[114:117], v[204:207], v[164:167], 0
	v_mfma_f32_16x16x32_bf16 v[102:105], v[196:199], v[172:175], 0
	v_mfma_f32_16x16x32_bf16 v[98:101], v[204:207], v[172:175], 0
	v_mfma_f32_16x16x32_bf16 v[84:87], v[196:199], v[180:183], 0
	v_mfma_f32_16x16x32_bf16 v[80:83], v[204:207], v[180:183], 0
	v_mfma_f32_16x16x32_bf16 v[68:71], v[196:199], v[188:191], 0
	v_mfma_f32_16x16x32_bf16 v[64:67], v[204:207], v[188:191], 0
	v_mfma_f32_16x16x32_bf16 v[118:121], v[200:203], v[168:171], v[118:121]
	v_mfma_f32_16x16x32_bf16 v[114:117], v[208:211], v[168:171], v[114:117]
	v_mfma_f32_16x16x32_bf16 v[102:105], v[200:203], v[176:179], v[102:105]
	v_mfma_f32_16x16x32_bf16 v[98:101], v[208:211], v[176:179], v[98:101]
	v_mfma_f32_16x16x32_bf16 v[84:87], v[200:203], v[184:187], v[84:87]
	v_mfma_f32_16x16x32_bf16 v[80:83], v[208:211], v[184:187], v[80:83]
	v_mfma_f32_16x16x32_bf16 v[68:71], v[200:203], v[192:195], v[68:71]
	v_mfma_f32_16x16x32_bf16 v[64:67], v[208:211], v[192:195], v[64:67]
	s_setprio 0
	s_mov_b32 m0, s26
	v_lshl_add_u64 v[214:215], s[38:39], 0, v[130:131]
	s_barrier
	ds_read_b128 v[164:167], v150 offset:16384
	ds_read_b128 v[168:171], v150 offset:17408
	ds_read_b128 v[172:175], v150 offset:18432
	ds_read_b128 v[176:179], v150 offset:19456
	ds_read_b128 v[180:183], v150 offset:20480
	ds_read_b128 v[184:187], v150 offset:21504
	ds_read_b128 v[188:191], v150 offset:22528
	ds_read_b128 v[192:195], v150 offset:23552
	global_load_lds_dwordx4 v[214:215], off
	v_lshl_add_u64 v[216:217], s[38:39], 0, v[132:133]
	s_mov_b32 m0, s27
	s_nop 0
	global_load_lds_dwordx4 v[216:217], off
	s_barrier
	s_waitcnt lgkmcnt(0)
	s_setprio 1
	s_waitcnt lgkmcnt(0)
	v_mfma_f32_16x16x32_bf16 v[60:63], v[140:143], v[164:167], 0
	v_mfma_f32_16x16x32_bf16 v[56:59], v[156:159], v[164:167], 0
	v_mfma_f32_16x16x32_bf16 v[44:47], v[140:143], v[172:175], 0
	v_mfma_f32_16x16x32_bf16 v[40:43], v[156:159], v[172:175], 0
	v_mfma_f32_16x16x32_bf16 v[28:31], v[140:143], v[180:183], 0
	v_mfma_f32_16x16x32_bf16 v[24:27], v[156:159], v[180:183], 0
	v_mfma_f32_16x16x32_bf16 v[12:15], v[140:143], v[188:191], 0
	v_mfma_f32_16x16x32_bf16 v[8:11], v[156:159], v[188:191], 0
	v_mfma_f32_16x16x32_bf16 v[60:63], v[152:155], v[168:171], v[60:63]
	v_mfma_f32_16x16x32_bf16 v[56:59], v[160:163], v[168:171], v[56:59]
	v_mfma_f32_16x16x32_bf16 v[44:47], v[152:155], v[176:179], v[44:47]
	v_mfma_f32_16x16x32_bf16 v[40:43], v[160:163], v[176:179], v[40:43]
	v_mfma_f32_16x16x32_bf16 v[28:31], v[152:155], v[184:187], v[28:31]
	v_mfma_f32_16x16x32_bf16 v[24:27], v[160:163], v[184:187], v[24:27]
	v_mfma_f32_16x16x32_bf16 v[12:15], v[152:155], v[192:195], v[12:15]
	v_mfma_f32_16x16x32_bf16 v[8:11], v[160:163], v[192:195], v[8:11]
	s_setprio 0
	s_barrier
	s_add_u32 s0, s24, 0x40000
	s_addc_u32 s1, s25, 0
	s_add_i32 s46, s47, s7
	v_lshl_add_u64 v[140:141], s[0:1], 0, v[96:97]
	s_mov_b32 m0, s46
	s_nop 0
	global_load_lds_dwordx4 v[140:141], off
	v_lshl_add_u64 v[140:141], s[0:1], 0, v[134:135]
	s_add_i32 m0, s46, 0x2000
	s_nop 0
	global_load_lds_dwordx4 v[140:141], off
	s_waitcnt vmcnt(6)
	s_barrier
	s_setprio 1
	v_mfma_f32_16x16x32_bf16 v[52:55], v[196:199], v[164:167], 0
	v_mfma_f32_16x16x32_bf16 v[48:51], v[204:207], v[164:167], 0
	v_mfma_f32_16x16x32_bf16 v[36:39], v[196:199], v[172:175], 0
	v_mfma_f32_16x16x32_bf16 v[32:35], v[204:207], v[172:175], 0
	v_mfma_f32_16x16x32_bf16 v[20:23], v[196:199], v[180:183], 0
	v_mfma_f32_16x16x32_bf16 v[16:19], v[204:207], v[180:183], 0
	v_mfma_f32_16x16x32_bf16 v[4:7], v[196:199], v[188:191], 0
	v_mfma_f32_16x16x32_bf16 v[0:3], v[204:207], v[188:191], 0
	v_mfma_f32_16x16x32_bf16 v[52:55], v[200:203], v[168:171], v[52:55]
	v_mfma_f32_16x16x32_bf16 v[48:51], v[208:211], v[168:171], v[48:51]
	v_mfma_f32_16x16x32_bf16 v[36:39], v[200:203], v[176:179], v[36:39]
	v_mfma_f32_16x16x32_bf16 v[32:35], v[208:211], v[176:179], v[32:35]
	v_mfma_f32_16x16x32_bf16 v[20:23], v[200:203], v[184:187], v[20:23]
	v_mfma_f32_16x16x32_bf16 v[16:19], v[208:211], v[184:187], v[16:19]
	v_mfma_f32_16x16x32_bf16 v[4:7], v[200:203], v[192:195], v[4:7]
	v_mfma_f32_16x16x32_bf16 v[0:3], v[208:211], v[192:195], v[0:3]
	s_setprio 0
	s_branch .Lkmid_26158

; #define PG8_STAGE(bufoff, gbase, voff) do { _Pragma("unroll") for (int _i = 0; _i < 2; ++_i) \
;         __builtin_amdgcn_global_load_lds((const unsigned*)((const char*)(gbase) + (voff)[_i]), (LAS unsigned*)(lds + (bufoff) + ldsw + _i * 8192), 16, 0, 0); } while (0)
; #define PG8_LDA(dst, b, h) do { _Pragma("unroll") for (int m = 0; m < 4; ++m) _Pragma("unroll") for (int k = 0; k < 2; ++k) dst[m][k] = *(const LAS bf16x8*)(lds + PG8_SA(b, h) + aoff + m * 2048 + k * 1024); } while (0)
; #define PG8_LDB(dst, b, h) do { _Pragma("unroll") for (int n = 0; n < 2; ++n) _Pragma("unroll") for (int k = 0; k < 2; ++k) dst[n][k] = *(const LAS bf16x8*)(lds + PG8_SB(b, h) + boff + n * 2048 + k * 1024); } while (0)
; #define PG8_MMA(ai, bj, At, Bt) do { __builtin_amdgcn_s_setprio(1); _Pragma("unroll") for (int m = 0; m < 4; ++m) _Pragma("unroll") for (int n = 0; n < 2; ++n) _Pragma("unroll") for (int k = 0; k < 2; ++k) \
;         acc[ai][bj][m][n] = __builtin_amdgcn_mfma_f32_16x16x32_bf16(Bt[n][k], At[m][k], acc[ai][bj][m][n], 0, 0, 0); __builtin_amdgcn_s_setprio(0); } while (0)
; #define PG8_WAIT_L(n) asm volatile("s_waitcnt lgkmcnt(" #n ")" ::: "memory")
; #define PG8_BAR __builtin_amdgcn_s_barrier()
; #define PG8_SCHED __builtin_amdgcn_sched_barrier(0)
; template <class Epi, class Sched>
; DI void gemm_phase(LAS unsigned char* lds, const Gemm g, const Sched& S, const Epi& E) {
;     ...
;             PG8_LDB(B0, 1, 0); PG8_SCHED; PG8_LDA(At, 1, 0); PG8_STAGE(PG8_SA(0, 1), a2 + hstep, voffA);
;             PG8_WAIT_L(8); PG8_BAR; PG8_WAIT_L(0); PG8_MMA(0, 0, At, B0); PG8_BAR; PG8_SCHED;
;             PG8_LDB(B1, 1, 1); PG8_STAGE(PG8_SB(1, 0), b3, voffB);
;             PG8_BAR; PG8_WAIT_L(0); PG8_MMA(0, 1, At, B1); PG8_BAR;
;             PG8_LDA(At, 1, 1); PG8_STAGE(PG8_SA(1, 0), a3, voffA);
;             PG8_BAR; PG8_WAIT_L(0); PG8_MMA(1, 0, At, B0); PG8_BAR; PG8_SCHED;
.Lkmid_26158:
	s_add_i32 s46, 0, 0x18000
	v_add_u32_e32 v151, s46, v147
	s_barrier
	ds_read_b128 v[140:143], v151
	ds_read_b128 v[152:155], v151 offset:1024
	ds_read_b128 v[156:159], v151 offset:2048
	ds_read_b128 v[160:163], v151 offset:3072
	s_add_u32 s0, s38, 0x40000
	s_addc_u32 s1, s39, 0
	s_mov_b32 m0, s28
	v_lshl_add_u64 v[196:197], s[0:1], 0, v[130:131]
	ds_read_b128 v[164:167], v150 offset:32768
	ds_read_b128 v[168:171], v150 offset:33792
	ds_read_b128 v[172:175], v150 offset:34816
	ds_read_b128 v[176:179], v150 offset:35840
	ds_read_b128 v[180:183], v150 offset:36864
	ds_read_b128 v[184:187], v150 offset:37888
	ds_read_b128 v[188:191], v150 offset:38912
	ds_read_b128 v[192:195], v150 offset:39936
	global_load_lds_dwordx4 v[196:197], off
	v_lshl_add_u64 v[196:197], s[0:1], 0, v[132:133]
	s_mov_b32 m0, s29
	s_nop 0
	global_load_lds_dwordx4 v[196:197], off
	s_waitcnt lgkmcnt(8)
	s_barrier
	s_waitcnt lgkmcnt(0)
	s_setprio 1
	s_waitcnt lgkmcnt(0)
	v_mfma_f32_16x16x32_bf16 v[126:129], v[140:143], v[164:167], v[126:129]
	v_mfma_f32_16x16x32_bf16 v[122:125], v[156:159], v[164:167], v[122:125]
	v_mfma_f32_16x16x32_bf16 v[110:113], v[140:143], v[172:175], v[110:113]
	v_mfma_f32_16x16x32_bf16 v[106:109], v[156:159], v[172:175], v[106:109]
	v_mfma_f32_16x16x32_bf16 v[92:95], v[140:143], v[180:183], v[92:95]
	v_mfma_f32_16x16x32_bf16 v[88:91], v[156:159], v[180:183], v[88:91]
	v_mfma_f32_16x16x32_bf16 v[76:79], v[140:143], v[188:191], v[76:79]
	v_mfma_f32_16x16x32_bf16 v[72:75], v[156:159], v[188:191], v[72:75]
	v_mfma_f32_16x16x32_bf16 v[126:129], v[152:155], v[168:171], v[126:129]
	v_mfma_f32_16x16x32_bf16 v[122:125], v[160:163], v[168:171], v[122:125]
	v_mfma_f32_16x16x32_bf16 v[110:113], v[152:155], v[176:179], v[110:113]
	v_mfma_f32_16x16x32_bf16 v[106:109], v[160:163], v[176:179], v[106:109]
	v_mfma_f32_16x16x32_bf16 v[92:95], v[152:155], v[184:187], v[92:95]
	v_mfma_f32_16x16x32_bf16 v[88:91], v[160:163], v[184:187], v[88:91]
	v_mfma_f32_16x16x32_bf16 v[76:79], v[152:155], v[192:195], v[76:79]
	v_mfma_f32_16x16x32_bf16 v[72:75], v[160:163], v[192:195], v[72:75]
	s_setprio 0
	s_barrier
	s_add_i32 s38, 0, 0x1c000
	s_add_i32 s0, s46, s7
	v_add_u32_e32 v151, s38, v147
	v_lshl_add_u64 v[144:145], v[144:145], 0, s[36:37]
	s_mov_b32 m0, s0
	ds_read_b128 v[196:199], v151
	ds_read_b128 v[200:203], v151 offset:1024
	ds_read_b128 v[204:207], v151 offset:2048
	ds_read_b128 v[208:211], v151 offset:3072
	global_load_lds_dwordx4 v[144:145], off
	v_lshl_add_u64 v[144:145], v[212:213], 0, s[36:37]
	s_add_i32 m0, s0, 0x2000
	s_nop 0
	global_load_lds_dwordx4 v[144:145], off
	s_barrier
	s_waitcnt lgkmcnt(0)
	s_setprio 1
	s_waitcnt lgkmcnt(0)
	v_mfma_f32_16x16x32_bf16 v[118:121], v[196:199], v[164:167], v[118:121]
	v_mfma_f32_16x16x32_bf16 v[114:117], v[204:207], v[164:167], v[114:117]
	v_mfma_f32_16x16x32_bf16 v[102:105], v[196:199], v[172:175], v[102:105]
	v_mfma_f32_16x16x32_bf16 v[98:101], v[204:207], v[172:175], v[98:101]
	v_mfma_f32_16x16x32_bf16 v[84:87], v[196:199], v[180:183], v[84:87]
	v_mfma_f32_16x16x32_bf16 v[80:83], v[204:207], v[180:183], v[80:83]
	v_mfma_f32_16x16x32_bf16 v[68:71], v[196:199], v[188:191], v[68:71]
	v_mfma_f32_16x16x32_bf16 v[64:67], v[204:207], v[188:191], v[64:67]
	v_mfma_f32_16x16x32_bf16 v[118:121], v[200:203], v[168:171], v[118:121]
	v_mfma_f32_16x16x32_bf16 v[114:117], v[208:211], v[168:171], v[114:117]
	v_mfma_f32_16x16x32_bf16 v[102:105], v[200:203], v[176:179], v[102:105]
	v_mfma_f32_16x16x32_bf16 v[98:101], v[208:211], v[176:179], v[98:101]
	v_mfma_f32_16x16x32_bf16 v[84:87], v[200:203], v[184:187], v[84:87]
	v_mfma_f32_16x16x32_bf16 v[80:83], v[208:211], v[184:187], v[80:83]
	v_mfma_f32_16x16x32_bf16 v[68:71], v[200:203], v[192:195], v[68:71]
	v_mfma_f32_16x16x32_bf16 v[64:67], v[208:211], v[192:195], v[64:67]
	s_setprio 0
	s_mov_b32 m0, s30
	v_lshl_add_u64 v[144:145], v[214:215], 0, s[36:37]
	s_barrier
	ds_read_b128 v[164:167], v150 offset:49152
	ds_read_b128 v[168:171], v150 offset:50176
	ds_read_b128 v[172:175], v150 offset:51200
	ds_read_b128 v[176:179], v150 offset:52224
	ds_read_b128 v[180:183], v150 offset:53248
	ds_read_b128 v[184:187], v150 offset:54272
	ds_read_b128 v[188:191], v150 offset:55296
	ds_read_b128 v[192:195], v150 offset:56320
	global_load_lds_dwordx4 v[144:145], off
	v_lshl_add_u64 v[144:145], v[216:217], 0, s[36:37]
	s_mov_b32 m0, s31
	s_nop 0
	global_load_lds_dwordx4 v[144:145], off
	s_barrier
	s_waitcnt lgkmcnt(0)
	s_setprio 1
	s_waitcnt lgkmcnt(0)
	v_mfma_f32_16x16x32_bf16 v[60:63], v[140:143], v[164:167], v[60:63]
	v_mfma_f32_16x16x32_bf16 v[56:59], v[156:159], v[164:167], v[56:59]
	v_mfma_f32_16x16x32_bf16 v[44:47], v[140:143], v[172:175], v[44:47]
	v_mfma_f32_16x16x32_bf16 v[40:43], v[156:159], v[172:175], v[40:43]
	v_mfma_f32_16x16x32_bf16 v[28:31], v[140:143], v[180:183], v[28:31]
	v_mfma_f32_16x16x32_bf16 v[24:27], v[156:159], v[180:183], v[24:27]
	v_mfma_f32_16x16x32_bf16 v[12:15], v[140:143], v[188:191], v[12:15]
	v_mfma_f32_16x16x32_bf16 v[8:11], v[156:159], v[188:191], v[8:11]
	v_mfma_f32_16x16x32_bf16 v[60:63], v[152:155], v[168:171], v[60:63]
	v_mfma_f32_16x16x32_bf16 v[56:59], v[160:163], v[168:171], v[56:59]
	v_mfma_f32_16x16x32_bf16 v[44:47], v[152:155], v[176:179], v[44:47]
	v_mfma_f32_16x16x32_bf16 v[40:43], v[160:163], v[176:179], v[40:43]
	v_mfma_f32_16x16x32_bf16 v[28:31], v[152:155], v[184:187], v[28:31]
	v_mfma_f32_16x16x32_bf16 v[24:27], v[160:163], v[184:187], v[24:27]
	v_mfma_f32_16x16x32_bf16 v[12:15], v[152:155], v[192:195], v[12:15]
	v_mfma_f32_16x16x32_bf16 v[8:11], v[160:163], v[192:195], v[8:11]
	s_setprio 0
	s_barrier
; #define LAS __attribute__((address_space(3)))
; DI unsigned pk2(float lo, float hi) { f32x2 v = {lo, hi}; hbf2 r = __builtin_convertvector(v, hbf2); return __builtin_bit_cast(unsigned, r); }
; #define PG8_STAGE(bufoff, gbase, voff) do { _Pragma("unroll") for (int _i = 0; _i < 2; ++_i) \
;         __builtin_amdgcn_global_load_lds((const unsigned*)((const char*)(gbase) + (voff)[_i]), (LAS unsigned*)(lds + (bufoff) + ldsw + _i * 8192), 16, 0, 0); } while (0)
; #define PG8_MMA(ai, bj, At, Bt) do { __builtin_amdgcn_s_setprio(1); _Pragma("unroll") for (int m = 0; m < 4; ++m) _Pragma("unroll") for (int n = 0; n < 2; ++n) _Pragma("unroll") for (int k = 0; k < 2; ++k) \
;         acc[ai][bj][m][n] = __builtin_amdgcn_mfma_f32_16x16x32_bf16(Bt[n][k], At[m][k], acc[ai][bj][m][n], 0, 0, 0); __builtin_amdgcn_s_setprio(0); } while (0)
; #define PG8_BAR __builtin_amdgcn_s_barrier()
; template <class Epi, class Sched>
; DI void gemm_phase(LAS unsigned char* lds, const Gemm g, const Sched& S, const Epi& E) {
;     ...
;             PG8_STAGE(PG8_SB(1, 1), b3 + hstep, voffB);
;             PG8_WAIT_V(6); PG8_BAR; PG8_MMA(1, 1, At, B1); PG8_BAR;
;         }
;         if (cur.part < 0) E(acc, cur, wr, wc, fr, fq, lds);
;     DI void operator()(f32x4 (&acc)[2][2][4][2], const Unit& u, int wr, int wc, int fr, int fq, LAS unsigned char* lds) const {
;         const int row0 = u.pm * 256 + wr * 64 + fr, hc = u.pn * 128 + wc * 32 + 8 * fq;
;         float rsv[8];
;         { const LAS float* tab = (const LAS float*)(lds + RS_OFF) + u.rk * 256 + wr * 64 + fr;
; #pragma unroll
;           for (int i = 0; i < 8; ++i) rsv[i] = tab[(i >> 2) * 128 + (i & 3) * 16]; }
; #pragma unroll
;         for (int ai = 0; ai < 2; ++ai)
; #pragma unroll
;             for (int m = 0; m < 4; ++m) {
;                 const int row = row0 + ai * 128 + m * 16; const float rs = rsv[ai * 4 + m];
;                 const f32x4 a0 = acc[ai][0][m][0] * rs, a1 = acc[ai][0][m][1] * rs, b0 = acc[ai][1][m][0] * rs, b1 = acc[ai][1][m][1] * rs;
;                 u32x4 w;
;                 w.x = pk2(silu_mul(a0[0], b0[0]), silu_mul(a0[1], b0[1])); w.y = pk2(silu_mul(a0[2], b0[2]), silu_mul(a0[3], b0[3]));
;                 w.z = pk2(silu_mul(a1[0], b1[0]), silu_mul(a1[1], b1[1])); w.w = pk2(silu_mul(a1[2], b1[2]), silu_mul(a1[3], b1[3]));
;                 *(u32x4*)(H + (size_t)row * DFF + hc) = w;
;             }
	s_add_u32 s0, s24, 0x40080
	s_addc_u32 s1, s25, 0
	s_add_i32 s24, s38, s7
	v_lshl_add_u64 v[140:141], s[0:1], 0, v[96:97]
	s_mov_b32 m0, s24
	s_nop 0
	global_load_lds_dwordx4 v[140:141], off
	v_lshl_add_u64 v[140:141], s[0:1], 0, v[134:135]
	s_add_i32 m0, s24, 0x2000
	s_nop 0
	global_load_lds_dwordx4 v[140:141], off
	s_waitcnt vmcnt(6)
	s_barrier
	s_setprio 1
	v_mfma_f32_16x16x32_bf16 v[52:55], v[196:199], v[164:167], v[52:55]
	v_mfma_f32_16x16x32_bf16 v[48:51], v[204:207], v[164:167], v[48:51]
	v_mfma_f32_16x16x32_bf16 v[36:39], v[196:199], v[172:175], v[36:39]
	v_mfma_f32_16x16x32_bf16 v[32:35], v[204:207], v[172:175], v[32:35]
	v_mfma_f32_16x16x32_bf16 v[20:23], v[196:199], v[180:183], v[20:23]
	v_mfma_f32_16x16x32_bf16 v[16:19], v[204:207], v[180:183], v[16:19]
	v_mfma_f32_16x16x32_bf16 v[4:7], v[196:199], v[188:191], v[4:7]
	v_mfma_f32_16x16x32_bf16 v[0:3], v[204:207], v[188:191], v[0:3]
	v_mfma_f32_16x16x32_bf16 v[52:55], v[200:203], v[168:171], v[52:55]
	v_mfma_f32_16x16x32_bf16 v[48:51], v[208:211], v[168:171], v[48:51]
	v_mfma_f32_16x16x32_bf16 v[36:39], v[200:203], v[176:179], v[36:39]
	v_mfma_f32_16x16x32_bf16 v[32:35], v[208:211], v[176:179], v[32:35]
	v_mfma_f32_16x16x32_bf16 v[20:23], v[200:203], v[184:187], v[20:23]
	v_mfma_f32_16x16x32_bf16 v[16:19], v[208:211], v[184:187], v[16:19]
	v_mfma_f32_16x16x32_bf16 v[4:7], v[200:203], v[192:195], v[4:7]
	v_mfma_f32_16x16x32_bf16 v[0:3], v[208:211], v[192:195], v[0:3]
	s_setprio 0
	s_add_i32 s45, s45, 2
	s_add_u32 s22, s22, 0x100
	s_addc_u32 s23, s23, 0
	s_add_u32 s43, s43, 0x100
	s_addc_u32 s44, s44, 0
	s_cmp_lt_u32 s45, 14
	s_barrier
	s_cbranch_scc1 .LBB0_1840
	v_lshl_add_u32 v140, s33, 10, v148
	ds_read2_b32 v[152:153], v140 offset1:16
	ds_read2_b32 v[144:145], v140 offset0:32 offset1:48
	ds_read2_b32 v[142:143], v140 offset0:128 offset1:144
	ds_read2_b32 v[140:141], v140 offset0:160 offset1:176
	v_lshl_or_b32 v154, s2, 7, v149
	v_lshl_add_u32 v151, s41, 8, v146
	v_lshlrev_b32_e32 v154, 1, v154
	v_mad_u32_u24 v155, v151, s35, v154
	s_mov_b64 s[22:23], -1
	s_andn2_b64 vcc, exec, s[16:17]
	s_waitcnt lgkmcnt(0)
	v_pk_mul_f32 v[126:127], v[126:127], v[152:153] op_sel_hi:[1,0]
	v_pk_mul_f32 v[128:129], v[128:129], v[152:153] op_sel_hi:[1,0]
	v_pk_mul_f32 v[122:123], v[122:123], v[152:153] op_sel_hi:[1,0]
	v_pk_mul_f32 v[124:125], v[124:125], v[152:153] op_sel_hi:[1,0]
	v_pk_mul_f32 v[118:119], v[118:119], v[152:153] op_sel_hi:[1,0]
	v_pk_mul_f32 v[120:121], v[120:121], v[152:153] op_sel_hi:[1,0]
	v_pk_mul_f32 v[114:115], v[114:115], v[152:153] op_sel_hi:[1,0]
	v_pk_mul_f32 v[116:117], v[116:117], v[152:153] op_sel_hi:[1,0]
	v_mul_f32_e32 v156, 0xbfb8aa3b, v126
	v_mul_f32_e32 v157, 0xbfb8aa3b, v127
	v_mul_f32_e32 v158, 0xbfb8aa3b, v128
	v_mul_f32_e32 v159, 0xbfb8aa3b, v129
	v_mul_f32_e32 v160, 0xbfb8aa3b, v122
	v_mul_f32_e32 v161, 0xbfb8aa3b, v123
	v_mul_f32_e32 v162, 0xbfb8aa3b, v124
	v_mul_f32_e32 v163, 0xbfb8aa3b, v125
	v_exp_f32_e32 v156, v156
	v_exp_f32_e32 v157, v157
	v_exp_f32_e32 v158, v158
	v_exp_f32_e32 v159, v159
	v_exp_f32_e32 v160, v160
	v_exp_f32_e32 v161, v161
	v_exp_f32_e32 v162, v162
	v_exp_f32_e32 v163, v163
	v_add_f32_e32 v156, 1.0, v156
	v_add_f32_e32 v157, 1.0, v157
	v_add_f32_e32 v158, 1.0, v158
	v_add_f32_e32 v159, 1.0, v159
	v_add_f32_e32 v160, 1.0, v160
	v_add_f32_e32 v161, 1.0, v161
	v_add_f32_e32 v162, 1.0, v162
	v_add_f32_e32 v163, 1.0, v163
	v_rcp_f32_e32 v156, v156
	v_rcp_f32_e32 v157, v157
	v_rcp_f32_e32 v158, v158
	v_rcp_f32_e32 v159, v159
	v_rcp_f32_e32 v160, v160
	v_rcp_f32_e32 v161, v161
	v_rcp_f32_e32 v162, v162
	v_rcp_f32_e32 v163, v163
	v_add_u32_e32 v172, 0x0, v155
	v_pk_mul_f32 v[126:127], v[126:127], v[156:157]
	v_pk_mul_f32 v[128:129], v[128:129], v[158:159]
	v_pk_mul_f32 v[122:123], v[122:123], v[160:161]
	v_pk_mul_f32 v[124:125], v[124:125], v[162:163]
	v_pk_mul_f32 v[118:119], v[118:119], v[126:127]
	v_pk_mul_f32 v[120:121], v[120:121], v[128:129]
	v_pk_mul_f32 v[114:115], v[114:115], v[122:123]
	v_pk_mul_f32 v[116:117], v[116:117], v[124:125]
	v_cvt_pk_bf16_f32 v164, v118, v119
	v_cvt_pk_bf16_f32 v165, v120, v121
	v_cvt_pk_bf16_f32 v166, v114, v115
	v_cvt_pk_bf16_f32 v167, v116, v117
	global_store_dwordx4 v172, v[164:167], s[74:75]
	v_pk_mul_f32 v[110:111], v[110:111], v[152:153] op_sel:[0,1]
	v_pk_mul_f32 v[112:113], v[112:113], v[152:153] op_sel:[0,1]
	v_pk_mul_f32 v[106:107], v[106:107], v[152:153] op_sel:[0,1]
	v_pk_mul_f32 v[108:109], v[108:109], v[152:153] op_sel:[0,1]
	v_pk_mul_f32 v[102:103], v[102:103], v[152:153] op_sel:[0,1]
	v_pk_mul_f32 v[104:105], v[104:105], v[152:153] op_sel:[0,1]
	v_pk_mul_f32 v[98:99], v[98:99], v[152:153] op_sel:[0,1]
	v_pk_mul_f32 v[100:101], v[100:101], v[152:153] op_sel:[0,1]
	v_mul_f32_e32 v156, 0xbfb8aa3b, v110
	v_mul_f32_e32 v157, 0xbfb8aa3b, v111
	v_mul_f32_e32 v158, 0xbfb8aa3b, v112
	v_mul_f32_e32 v159, 0xbfb8aa3b, v113
	v_mul_f32_e32 v160, 0xbfb8aa3b, v106
	v_mul_f32_e32 v161, 0xbfb8aa3b, v107
	v_mul_f32_e32 v162, 0xbfb8aa3b, v108
	v_mul_f32_e32 v163, 0xbfb8aa3b, v109
	v_exp_f32_e32 v156, v156
	v_exp_f32_e32 v157, v157
	v_exp_f32_e32 v158, v158
	v_exp_f32_e32 v159, v159
	v_exp_f32_e32 v160, v160
	v_exp_f32_e32 v161, v161
	v_exp_f32_e32 v162, v162
	v_exp_f32_e32 v163, v163
	v_add_f32_e32 v156, 1.0, v156
	v_add_f32_e32 v157, 1.0, v157
	v_add_f32_e32 v158, 1.0, v158
	v_add_f32_e32 v159, 1.0, v159
	v_add_f32_e32 v160, 1.0, v160
	v_add_f32_e32 v161, 1.0, v161
	v_add_f32_e32 v162, 1.0, v162
	v_add_f32_e32 v163, 1.0, v163
	v_rcp_f32_e32 v156, v156
	v_rcp_f32_e32 v157, v157
	v_rcp_f32_e32 v158, v158
	v_rcp_f32_e32 v159, v159
	v_rcp_f32_e32 v160, v160
	v_rcp_f32_e32 v161, v161
	v_rcp_f32_e32 v162, v162
; DI unsigned pk2(float lo, float hi) { f32x2 v = {lo, hi}; hbf2 r = __builtin_convertvector(v, hbf2); return __builtin_bit_cast(unsigned, r); }
; DI float silu_mul(float a, float b) { return a * fast_rcp(1.0f + fast_exp2(-a * LOG2E)) * b; }
;     DI void operator()(f32x4 (&acc)[2][2][4][2], const Unit& u, int wr, int wc, int fr, int fq, LAS unsigned char* lds) const {
;     ...
;         for (int ai = 0; ai < 2; ++ai)
; #pragma unroll
;             for (int m = 0; m < 4; ++m) {
;                 const int row = row0 + ai * 128 + m * 16; const float rs = rsv[ai * 4 + m];
;                 const f32x4 a0 = acc[ai][0][m][0] * rs, a1 = acc[ai][0][m][1] * rs, b0 = acc[ai][1][m][0] * rs, b1 = acc[ai][1][m][1] * rs;
;                 u32x4 w;
;                 w.x = pk2(silu_mul(a0[0], b0[0]), silu_mul(a0[1], b0[1])); w.y = pk2(silu_mul(a0[2], b0[2]), silu_mul(a0[3], b0[3]));
;                 w.z = pk2(silu_mul(a1[0], b1[0]), silu_mul(a1[1], b1[1])); w.w = pk2(silu_mul(a1[2], b1[2]), silu_mul(a1[3], b1[3]));
;                 *(u32x4*)(H + (size_t)row * DFF + hc) = w;
;             }
	v_rcp_f32_e32 v163, v163
	v_add_u32_e32 v172, 0x16000, v155
	v_pk_mul_f32 v[110:111], v[110:111], v[156:157]
	v_pk_mul_f32 v[112:113], v[112:113], v[158:159]
	v_pk_mul_f32 v[106:107], v[106:107], v[160:161]
	v_pk_mul_f32 v[108:109], v[108:109], v[162:163]
	v_pk_mul_f32 v[102:103], v[102:103], v[110:111]
	v_pk_mul_f32 v[104:105], v[104:105], v[112:113]
	v_pk_mul_f32 v[98:99], v[98:99], v[106:107]
	v_pk_mul_f32 v[100:101], v[100:101], v[108:109]
	v_cvt_pk_bf16_f32 v168, v102, v103
	v_cvt_pk_bf16_f32 v169, v104, v105
	v_cvt_pk_bf16_f32 v170, v98, v99
	v_cvt_pk_bf16_f32 v171, v100, v101
	global_store_dwordx4 v172, v[168:171], s[74:75]
	v_pk_mul_f32 v[92:93], v[92:93], v[144:145] op_sel_hi:[1,0]
	v_pk_mul_f32 v[94:95], v[94:95], v[144:145] op_sel_hi:[1,0]
	v_pk_mul_f32 v[88:89], v[88:89], v[144:145] op_sel_hi:[1,0]
	v_pk_mul_f32 v[90:91], v[90:91], v[144:145] op_sel_hi:[1,0]
	v_pk_mul_f32 v[84:85], v[84:85], v[144:145] op_sel_hi:[1,0]
	v_pk_mul_f32 v[86:87], v[86:87], v[144:145] op_sel_hi:[1,0]
	v_pk_mul_f32 v[80:81], v[80:81], v[144:145] op_sel_hi:[1,0]
	v_pk_mul_f32 v[82:83], v[82:83], v[144:145] op_sel_hi:[1,0]
	v_mul_f32_e32 v156, 0xbfb8aa3b, v92
	v_mul_f32_e32 v157, 0xbfb8aa3b, v93
	v_mul_f32_e32 v158, 0xbfb8aa3b, v94
	v_mul_f32_e32 v159, 0xbfb8aa3b, v95
	v_mul_f32_e32 v160, 0xbfb8aa3b, v88
	v_mul_f32_e32 v161, 0xbfb8aa3b, v89
	v_mul_f32_e32 v162, 0xbfb8aa3b, v90
	v_mul_f32_e32 v163, 0xbfb8aa3b, v91
	v_exp_f32_e32 v156, v156
	v_exp_f32_e32 v157, v157
	v_exp_f32_e32 v158, v158
	v_exp_f32_e32 v159, v159
	v_exp_f32_e32 v160, v160
	v_exp_f32_e32 v161, v161
	v_exp_f32_e32 v162, v162
	v_exp_f32_e32 v163, v163
	v_add_f32_e32 v156, 1.0, v156
	v_add_f32_e32 v157, 1.0, v157
	v_add_f32_e32 v158, 1.0, v158
	v_add_f32_e32 v159, 1.0, v159
	v_add_f32_e32 v160, 1.0, v160
	v_add_f32_e32 v161, 1.0, v161
	v_add_f32_e32 v162, 1.0, v162
	v_add_f32_e32 v163, 1.0, v163
	v_rcp_f32_e32 v156, v156
	v_rcp_f32_e32 v157, v157
	v_rcp_f32_e32 v158, v158
	v_rcp_f32_e32 v159, v159
	v_rcp_f32_e32 v160, v160
	v_rcp_f32_e32 v161, v161
	v_rcp_f32_e32 v162, v162
	v_rcp_f32_e32 v163, v163
	v_add_u32_e32 v172, 0x2c000, v155
	v_pk_mul_f32 v[92:93], v[92:93], v[156:157]
	v_pk_mul_f32 v[94:95], v[94:95], v[158:159]
	v_pk_mul_f32 v[88:89], v[88:89], v[160:161]
	v_pk_mul_f32 v[90:91], v[90:91], v[162:163]
	v_pk_mul_f32 v[84:85], v[84:85], v[92:93]
	v_pk_mul_f32 v[86:87], v[86:87], v[94:95]
	v_pk_mul_f32 v[80:81], v[80:81], v[88:89]
	v_pk_mul_f32 v[82:83], v[82:83], v[90:91]
	v_cvt_pk_bf16_f32 v164, v84, v85
	v_cvt_pk_bf16_f32 v165, v86, v87
	v_cvt_pk_bf16_f32 v166, v80, v81
	v_cvt_pk_bf16_f32 v167, v82, v83
	global_store_dwordx4 v172, v[164:167], s[74:75]
	v_pk_mul_f32 v[76:77], v[76:77], v[144:145] op_sel:[0,1]
	v_pk_mul_f32 v[78:79], v[78:79], v[144:145] op_sel:[0,1]
	v_pk_mul_f32 v[72:73], v[72:73], v[144:145] op_sel:[0,1]
	v_pk_mul_f32 v[74:75], v[74:75], v[144:145] op_sel:[0,1]
	v_pk_mul_f32 v[68:69], v[68:69], v[144:145] op_sel:[0,1]
	v_pk_mul_f32 v[70:71], v[70:71], v[144:145] op_sel:[0,1]
	v_pk_mul_f32 v[64:65], v[64:65], v[144:145] op_sel:[0,1]
	v_pk_mul_f32 v[66:67], v[66:67], v[144:145] op_sel:[0,1]
	v_mul_f32_e32 v156, 0xbfb8aa3b, v76
	v_mul_f32_e32 v157, 0xbfb8aa3b, v77
	v_mul_f32_e32 v158, 0xbfb8aa3b, v78
	v_mul_f32_e32 v159, 0xbfb8aa3b, v79
	v_mul_f32_e32 v160, 0xbfb8aa3b, v72
	v_mul_f32_e32 v161, 0xbfb8aa3b, v73
	v_mul_f32_e32 v162, 0xbfb8aa3b, v74
	v_mul_f32_e32 v163, 0xbfb8aa3b, v75
	v_exp_f32_e32 v156, v156
	v_exp_f32_e32 v157, v157
	v_exp_f32_e32 v158, v158
	v_exp_f32_e32 v159, v159
	v_exp_f32_e32 v160, v160
	v_exp_f32_e32 v161, v161
	v_exp_f32_e32 v162, v162
	v_exp_f32_e32 v163, v163
	v_add_f32_e32 v156, 1.0, v156
	v_add_f32_e32 v157, 1.0, v157
	v_add_f32_e32 v158, 1.0, v158
	v_add_f32_e32 v159, 1.0, v159
	v_add_f32_e32 v160, 1.0, v160
	v_add_f32_e32 v161, 1.0, v161
	v_add_f32_e32 v162, 1.0, v162
	v_add_f32_e32 v163, 1.0, v163
	v_rcp_f32_e32 v156, v156
	v_rcp_f32_e32 v157, v157
	v_rcp_f32_e32 v158, v158
	v_rcp_f32_e32 v159, v159
	v_rcp_f32_e32 v160, v160
	v_rcp_f32_e32 v161, v161
	v_rcp_f32_e32 v162, v162
	v_rcp_f32_e32 v163, v163
	v_add_u32_e32 v172, 0x42000, v155
	v_pk_mul_f32 v[76:77], v[76:77], v[156:157]
	v_pk_mul_f32 v[78:79], v[78:79], v[158:159]
	v_pk_mul_f32 v[72:73], v[72:73], v[160:161]
	v_pk_mul_f32 v[74:75], v[74:75], v[162:163]
	v_pk_mul_f32 v[68:69], v[68:69], v[76:77]
	v_pk_mul_f32 v[70:71], v[70:71], v[78:79]
	v_pk_mul_f32 v[64:65], v[64:65], v[72:73]
	v_pk_mul_f32 v[66:67], v[66:67], v[74:75]
	v_cvt_pk_bf16_f32 v168, v68, v69
	v_cvt_pk_bf16_f32 v169, v70, v71
	v_cvt_pk_bf16_f32 v170, v64, v65
	v_cvt_pk_bf16_f32 v171, v66, v67
	global_store_dwordx4 v172, v[168:171], s[74:75]
	v_pk_mul_f32 v[60:61], v[60:61], v[142:143] op_sel_hi:[1,0]
	v_pk_mul_f32 v[62:63], v[62:63], v[142:143] op_sel_hi:[1,0]
	v_pk_mul_f32 v[56:57], v[56:57], v[142:143] op_sel_hi:[1,0]
	v_pk_mul_f32 v[58:59], v[58:59], v[142:143] op_sel_hi:[1,0]
	v_pk_mul_f32 v[52:53], v[52:53], v[142:143] op_sel_hi:[1,0]
	v_pk_mul_f32 v[54:55], v[54:55], v[142:143] op_sel_hi:[1,0]
	v_pk_mul_f32 v[48:49], v[48:49], v[142:143] op_sel_hi:[1,0]
	v_pk_mul_f32 v[50:51], v[50:51], v[142:143] op_sel_hi:[1,0]
	v_mul_f32_e32 v156, 0xbfb8aa3b, v60
	v_mul_f32_e32 v157, 0xbfb8aa3b, v61
	v_mul_f32_e32 v158, 0xbfb8aa3b, v62
	v_mul_f32_e32 v159, 0xbfb8aa3b, v63
	v_mul_f32_e32 v160, 0xbfb8aa3b, v56
	v_mul_f32_e32 v161, 0xbfb8aa3b, v57
	v_mul_f32_e32 v162, 0xbfb8aa3b, v58
	v_mul_f32_e32 v163, 0xbfb8aa3b, v59
	v_exp_f32_e32 v156, v156
	v_exp_f32_e32 v157, v157
	v_exp_f32_e32 v158, v158
	v_exp_f32_e32 v159, v159
	v_exp_f32_e32 v160, v160
	v_exp_f32_e32 v161, v161
	v_exp_f32_e32 v162, v162
	v_exp_f32_e32 v163, v163
; DI unsigned pk2(float lo, float hi) { f32x2 v = {lo, hi}; hbf2 r = __builtin_convertvector(v, hbf2); return __builtin_bit_cast(unsigned, r); }
; DI float silu_mul(float a, float b) { return a * fast_rcp(1.0f + fast_exp2(-a * LOG2E)) * b; }
;     DI void operator()(f32x4 (&acc)[2][2][4][2], const Unit& u, int wr, int wc, int fr, int fq, LAS unsigned char* lds) const {
;     ...
;         for (int ai = 0; ai < 2; ++ai)
; #pragma unroll
;             for (int m = 0; m < 4; ++m) {
;                 const int row = row0 + ai * 128 + m * 16; const float rs = rsv[ai * 4 + m];
;                 const f32x4 a0 = acc[ai][0][m][0] * rs, a1 = acc[ai][0][m][1] * rs, b0 = acc[ai][1][m][0] * rs, b1 = acc[ai][1][m][1] * rs;
;                 u32x4 w;
;                 w.x = pk2(silu_mul(a0[0], b0[0]), silu_mul(a0[1], b0[1])); w.y = pk2(silu_mul(a0[2], b0[2]), silu_mul(a0[3], b0[3]));
;                 w.z = pk2(silu_mul(a1[0], b1[0]), silu_mul(a1[1], b1[1])); w.w = pk2(silu_mul(a1[2], b1[2]), silu_mul(a1[3], b1[3]));
;                 *(u32x4*)(H + (size_t)row * DFF + hc) = w;
;             }
	v_add_f32_e32 v156, 1.0, v156
	v_add_f32_e32 v157, 1.0, v157
	v_add_f32_e32 v158, 1.0, v158
	v_add_f32_e32 v159, 1.0, v159
	v_add_f32_e32 v160, 1.0, v160
	v_add_f32_e32 v161, 1.0, v161
	v_add_f32_e32 v162, 1.0, v162
	v_add_f32_e32 v163, 1.0, v163
	v_rcp_f32_e32 v156, v156
	v_rcp_f32_e32 v157, v157
	v_rcp_f32_e32 v158, v158
	v_rcp_f32_e32 v159, v159
	v_rcp_f32_e32 v160, v160
	v_rcp_f32_e32 v161, v161
	v_rcp_f32_e32 v162, v162
	v_rcp_f32_e32 v163, v163
	v_add_u32_e32 v172, 0xb0000, v155
	v_pk_mul_f32 v[60:61], v[60:61], v[156:157]
	v_pk_mul_f32 v[62:63], v[62:63], v[158:159]
	v_pk_mul_f32 v[56:57], v[56:57], v[160:161]
	v_pk_mul_f32 v[58:59], v[58:59], v[162:163]
	v_pk_mul_f32 v[52:53], v[52:53], v[60:61]
	v_pk_mul_f32 v[54:55], v[54:55], v[62:63]
	v_pk_mul_f32 v[48:49], v[48:49], v[56:57]
	v_pk_mul_f32 v[50:51], v[50:51], v[58:59]
	v_cvt_pk_bf16_f32 v164, v52, v53
	v_cvt_pk_bf16_f32 v165, v54, v55
	v_cvt_pk_bf16_f32 v166, v48, v49
	v_cvt_pk_bf16_f32 v167, v50, v51
	global_store_dwordx4 v172, v[164:167], s[74:75]
	v_pk_mul_f32 v[44:45], v[44:45], v[142:143] op_sel:[0,1]
	v_pk_mul_f32 v[46:47], v[46:47], v[142:143] op_sel:[0,1]
	v_pk_mul_f32 v[40:41], v[40:41], v[142:143] op_sel:[0,1]
	v_pk_mul_f32 v[42:43], v[42:43], v[142:143] op_sel:[0,1]
	v_pk_mul_f32 v[36:37], v[36:37], v[142:143] op_sel:[0,1]
	v_pk_mul_f32 v[38:39], v[38:39], v[142:143] op_sel:[0,1]
	v_pk_mul_f32 v[32:33], v[32:33], v[142:143] op_sel:[0,1]
	v_pk_mul_f32 v[34:35], v[34:35], v[142:143] op_sel:[0,1]
	v_mul_f32_e32 v156, 0xbfb8aa3b, v44
	v_mul_f32_e32 v157, 0xbfb8aa3b, v45
	v_mul_f32_e32 v158, 0xbfb8aa3b, v46
	v_mul_f32_e32 v159, 0xbfb8aa3b, v47
	v_mul_f32_e32 v160, 0xbfb8aa3b, v40
	v_mul_f32_e32 v161, 0xbfb8aa3b, v41
	v_mul_f32_e32 v162, 0xbfb8aa3b, v42
	v_mul_f32_e32 v163, 0xbfb8aa3b, v43
	v_exp_f32_e32 v156, v156
	v_exp_f32_e32 v157, v157
	v_exp_f32_e32 v158, v158
	v_exp_f32_e32 v159, v159
	v_exp_f32_e32 v160, v160
	v_exp_f32_e32 v161, v161
	v_exp_f32_e32 v162, v162
	v_exp_f32_e32 v163, v163
	v_add_f32_e32 v156, 1.0, v156
	v_add_f32_e32 v157, 1.0, v157
	v_add_f32_e32 v158, 1.0, v158
	v_add_f32_e32 v159, 1.0, v159
	v_add_f32_e32 v160, 1.0, v160
	v_add_f32_e32 v161, 1.0, v161
	v_add_f32_e32 v162, 1.0, v162
	v_add_f32_e32 v163, 1.0, v163
	v_rcp_f32_e32 v156, v156
	v_rcp_f32_e32 v157, v157
	v_rcp_f32_e32 v158, v158
	v_rcp_f32_e32 v159, v159
	v_rcp_f32_e32 v160, v160
	v_rcp_f32_e32 v161, v161
	v_rcp_f32_e32 v162, v162
	v_rcp_f32_e32 v163, v163
	v_add_u32_e32 v172, 0xc6000, v155
	v_pk_mul_f32 v[44:45], v[44:45], v[156:157]
	v_pk_mul_f32 v[46:47], v[46:47], v[158:159]
	v_pk_mul_f32 v[40:41], v[40:41], v[160:161]
	v_pk_mul_f32 v[42:43], v[42:43], v[162:163]
	v_pk_mul_f32 v[36:37], v[36:37], v[44:45]
	v_pk_mul_f32 v[38:39], v[38:39], v[46:47]
	v_pk_mul_f32 v[32:33], v[32:33], v[40:41]
	v_pk_mul_f32 v[34:35], v[34:35], v[42:43]
	v_cvt_pk_bf16_f32 v168, v36, v37
	v_cvt_pk_bf16_f32 v169, v38, v39
	v_cvt_pk_bf16_f32 v170, v32, v33
	v_cvt_pk_bf16_f32 v171, v34, v35
	global_store_dwordx4 v172, v[168:171], s[74:75]
	v_pk_mul_f32 v[28:29], v[28:29], v[140:141] op_sel_hi:[1,0]
	v_pk_mul_f32 v[30:31], v[30:31], v[140:141] op_sel_hi:[1,0]
	v_pk_mul_f32 v[24:25], v[24:25], v[140:141] op_sel_hi:[1,0]
	v_pk_mul_f32 v[26:27], v[26:27], v[140:141] op_sel_hi:[1,0]
	v_pk_mul_f32 v[20:21], v[20:21], v[140:141] op_sel_hi:[1,0]
	v_pk_mul_f32 v[22:23], v[22:23], v[140:141] op_sel_hi:[1,0]
	v_pk_mul_f32 v[16:17], v[16:17], v[140:141] op_sel_hi:[1,0]
	v_pk_mul_f32 v[18:19], v[18:19], v[140:141] op_sel_hi:[1,0]
	v_mul_f32_e32 v156, 0xbfb8aa3b, v28
	v_mul_f32_e32 v157, 0xbfb8aa3b, v29
	v_mul_f32_e32 v158, 0xbfb8aa3b, v30
	v_mul_f32_e32 v159, 0xbfb8aa3b, v31
	v_mul_f32_e32 v160, 0xbfb8aa3b, v24
	v_mul_f32_e32 v161, 0xbfb8aa3b, v25
	v_mul_f32_e32 v162, 0xbfb8aa3b, v26
	v_mul_f32_e32 v163, 0xbfb8aa3b, v27
	v_exp_f32_e32 v156, v156
	v_exp_f32_e32 v157, v157
	v_exp_f32_e32 v158, v158
	v_exp_f32_e32 v159, v159
	v_exp_f32_e32 v160, v160
	v_exp_f32_e32 v161, v161
	v_exp_f32_e32 v162, v162
	v_exp_f32_e32 v163, v163
	v_add_f32_e32 v156, 1.0, v156
	v_add_f32_e32 v157, 1.0, v157
	v_add_f32_e32 v158, 1.0, v158
	v_add_f32_e32 v159, 1.0, v159
	v_add_f32_e32 v160, 1.0, v160
	v_add_f32_e32 v161, 1.0, v161
	v_add_f32_e32 v162, 1.0, v162
	v_add_f32_e32 v163, 1.0, v163
	v_rcp_f32_e32 v156, v156
	v_rcp_f32_e32 v157, v157
	v_rcp_f32_e32 v158, v158
	v_rcp_f32_e32 v159, v159
	v_rcp_f32_e32 v160, v160
	v_rcp_f32_e32 v161, v161
	v_rcp_f32_e32 v162, v162
	v_rcp_f32_e32 v163, v163
	v_add_u32_e32 v172, 0xdc000, v155
	v_pk_mul_f32 v[28:29], v[28:29], v[156:157]
	v_pk_mul_f32 v[30:31], v[30:31], v[158:159]
	v_pk_mul_f32 v[24:25], v[24:25], v[160:161]
	v_pk_mul_f32 v[26:27], v[26:27], v[162:163]
	v_pk_mul_f32 v[20:21], v[20:21], v[28:29]
	v_pk_mul_f32 v[22:23], v[22:23], v[30:31]
	v_pk_mul_f32 v[16:17], v[16:17], v[24:25]
	v_pk_mul_f32 v[18:19], v[18:19], v[26:27]
	v_cvt_pk_bf16_f32 v164, v20, v21
	v_cvt_pk_bf16_f32 v165, v22, v23
	v_cvt_pk_bf16_f32 v166, v16, v17
	v_cvt_pk_bf16_f32 v167, v18, v19
	global_store_dwordx4 v172, v[164:167], s[74:75]
	v_pk_mul_f32 v[12:13], v[12:13], v[140:141] op_sel:[0,1]
	v_pk_mul_f32 v[14:15], v[14:15], v[140:141] op_sel:[0,1]
	v_pk_mul_f32 v[8:9], v[8:9], v[140:141] op_sel:[0,1]
	v_pk_mul_f32 v[10:11], v[10:11], v[140:141] op_sel:[0,1]
	v_pk_mul_f32 v[4:5], v[4:5], v[140:141] op_sel:[0,1]
	v_pk_mul_f32 v[6:7], v[6:7], v[140:141] op_sel:[0,1]
	v_pk_mul_f32 v[0:1], v[0:1], v[140:141] op_sel:[0,1]
	v_pk_mul_f32 v[2:3], v[2:3], v[140:141] op_sel:[0,1]
	v_mul_f32_e32 v156, 0xbfb8aa3b, v12
	v_mul_f32_e32 v157, 0xbfb8aa3b, v13
	v_mul_f32_e32 v158, 0xbfb8aa3b, v14
	v_mul_f32_e32 v159, 0xbfb8aa3b, v15
	v_mul_f32_e32 v160, 0xbfb8aa3b, v8
	v_mul_f32_e32 v161, 0xbfb8aa3b, v9
	v_mul_f32_e32 v162, 0xbfb8aa3b, v10
	v_mul_f32_e32 v163, 0xbfb8aa3b, v11
	v_exp_f32_e32 v156, v156
	v_exp_f32_e32 v157, v157
	v_exp_f32_e32 v158, v158
	v_exp_f32_e32 v159, v159
	v_exp_f32_e32 v160, v160
	v_exp_f32_e32 v161, v161
	v_exp_f32_e32 v162, v162
	v_exp_f32_e32 v163, v163
	v_add_f32_e32 v156, 1.0, v156
	v_add_f32_e32 v157, 1.0, v157
	v_add_f32_e32 v158, 1.0, v158
	v_add_f32_e32 v159, 1.0, v159
	v_add_f32_e32 v160, 1.0, v160
	v_add_f32_e32 v161, 1.0, v161
	v_add_f32_e32 v162, 1.0, v162
	v_add_f32_e32 v163, 1.0, v163
	v_rcp_f32_e32 v156, v156
	v_rcp_f32_e32 v157, v157
	v_rcp_f32_e32 v158, v158
	v_rcp_f32_e32 v159, v159
	v_rcp_f32_e32 v160, v160
	v_rcp_f32_e32 v161, v161
	v_rcp_f32_e32 v162, v162
	v_rcp_f32_e32 v163, v163
	v_add_u32_e32 v172, 0xf2000, v155
	v_pk_mul_f32 v[12:13], v[12:13], v[156:157]
	v_pk_mul_f32 v[14:15], v[14:15], v[158:159]
	v_pk_mul_f32 v[8:9], v[8:9], v[160:161]
	v_pk_mul_f32 v[10:11], v[10:11], v[162:163]
	v_pk_mul_f32 v[4:5], v[4:5], v[12:13]
	v_pk_mul_f32 v[6:7], v[6:7], v[14:15]
	v_pk_mul_f32 v[0:1], v[0:1], v[8:9]
	v_pk_mul_f32 v[2:3], v[2:3], v[10:11]
	v_cvt_pk_bf16_f32 v168, v4, v5
	v_cvt_pk_bf16_f32 v169, v6, v7
	v_cvt_pk_bf16_f32 v170, v0, v1
	v_cvt_pk_bf16_f32 v171, v2, v3
	global_store_dwordx4 v172, v[168:171], s[74:75]
	s_cbranch_vccnz .LBB0_1831
; template <class Epi, class Sched>
; DI void gemm_phase(LAS unsigned char* lds, const Gemm g, const Sched& S, const Epi& E) {
;     ...
;         nxt.rk = cur.rk + (nxt.pm != cur.pm ? 1 : 0);
;         cur = nxt; cA = nA; cB = nB; ++ui;
	s_cmp_lg_u32 s14, s41
	s_cselect_b64 s[0:1], -1, 0
	s_cmp_lg_u64 s[0:1], 0
	s_addc_u32 s33, s33, 0
	s_mov_b64 s[22:23], 0
	s_branch .LBB0_1831

; #define PG8_STAGE(bufoff, gbase, voff) do { _Pragma("unroll") for (int _i = 0; _i < 2; ++_i) \
;         __builtin_amdgcn_global_load_lds((const unsigned*)((const char*)(gbase) + (voff)[_i]), (LAS unsigned*)(lds + (bufoff) + ldsw + _i * 8192), 16, 0, 0); } while (0)
; #define PG8_LDA(dst, b, h) do { _Pragma("unroll") for (int m = 0; m < 4; ++m) _Pragma("unroll") for (int k = 0; k < 2; ++k) dst[m][k] = *(const LAS bf16x8*)(lds + PG8_SA(b, h) + aoff + m * 2048 + k * 1024); } while (0)
; #define PG8_LDB(dst, b, h) do { _Pragma("unroll") for (int n = 0; n < 2; ++n) _Pragma("unroll") for (int k = 0; k < 2; ++k) dst[n][k] = *(const LAS bf16x8*)(lds + PG8_SB(b, h) + boff + n * 2048 + k * 1024); } while (0)
; #define PG8_MMA(ai, bj, At, Bt) do { __builtin_amdgcn_s_setprio(1); _Pragma("unroll") for (int m = 0; m < 4; ++m) _Pragma("unroll") for (int n = 0; n < 2; ++n) _Pragma("unroll") for (int k = 0; k < 2; ++k) \
;         acc[ai][bj][m][n] = __builtin_amdgcn_mfma_f32_16x16x32_bf16(Bt[n][k], At[m][k], acc[ai][bj][m][n], 0, 0, 0); __builtin_amdgcn_s_setprio(0); } while (0)
; #define PG8_WAIT_L(n) asm volatile("s_waitcnt lgkmcnt(" #n ")" ::: "memory")
; template <class Epi, class Sched>
; DI void gemm_phase(LAS unsigned char* lds, const Gemm g, const Sched& S, const Epi& E) {
;     ...
;         const char* nA = has_next ? (const char*)g.A + (size_t)nxt.pm * tstep + (size_t)nxt.kt0 * kstep : cA; const char* nB = has_next ? (const char*)g.Bt + (size_t)nxt.pn * tstep + (size_t)nxt.kt0 * kstep : cB;
;         const int nt = cur.nkt;
;         for (int t = 0; t < nt; t += 2) {
;             const bool last = (t == nt - 2);
;             const char* a1 = cA + (size_t)(t + 1) * kstep;
;             const char* a2 = last ? nA : cA + (size_t)(t + 2) * kstep; const char* b2 = last ? nB : cB + (size_t)(t + 2) * kstep;
;             const char* a3 = a2 + kstep; const char* b3 = b2 + kstep;
;             PG8_LDB(B0, 0, 0); PG8_SCHED; PG8_LDA(At, 0, 0); PG8_STAGE(PG8_SA(1, 1), a1 + hstep, voffA);
;             PG8_WAIT_L(8); PG8_BAR; PG8_WAIT_L(0); PG8_MMA(0, 0, At, B0); PG8_BAR; PG8_SCHED;
;             PG8_LDB(B1, 0, 1); PG8_STAGE(PG8_SB(0, 0), b2, voffB);
;             PG8_BAR; PG8_WAIT_L(0); PG8_MMA(0, 1, At, B1); PG8_BAR;
;             PG8_LDA(At, 0, 1); PG8_STAGE(PG8_SA(0, 0), a2, voffA);
;             PG8_BAR; PG8_WAIT_L(0); PG8_MMA(1, 0, At, B0); PG8_BAR; PG8_SCHED;
.LBB0_1956:
	s_add_u32 s34, s20, 0x100
	v_mov_b32_e32 v0, 0
	s_addc_u32 s38, s21, 0
	s_mov_b32 s39, -2
	s_waitcnt lgkmcnt(0)
	s_waitcnt lgkmcnt(0)
	s_waitcnt vmcnt(0)
	s_add_u32 s20, s18, 0x100
	s_addc_u32 s21, s19, 0
	s_add_i32 s0, 0, 0x10000
	v_add_u32_e32 v142, s0, v213
	ds_read_b128 v[130:133], v142
	ds_read_b128 v[134:137], v142 offset:1024
	ds_read_b128 v[138:141], v142 offset:2048
	ds_read_b128 v[142:145], v142 offset:3072
	s_cmp_eq_u32 s39, 40
	s_cselect_b32 s25, s15, s21
	s_cselect_b32 s24, s14, s20
	s_cselect_b32 s23, s17, s38
	s_cselect_b32 s22, s16, s34
	v_lshl_add_u64 v[178:179], s[18:19], 0, v[192:193]
	s_add_i32 m0, s28, 0xc000
	ds_read_b128 v[146:149], v215
	ds_read_b128 v[150:153], v215 offset:1024
	ds_read_b128 v[154:157], v215 offset:2048
	ds_read_b128 v[158:161], v215 offset:3072
	ds_read_b128 v[162:165], v215 offset:4096
	ds_read_b128 v[166:169], v215 offset:5120
	ds_read_b128 v[170:173], v215 offset:6144
	ds_read_b128 v[174:177], v215 offset:7168
	global_load_lds_dwordx4 v[178:179], off
	v_lshl_add_u64 v[178:179], s[18:19], 0, v[194:195]
	s_add_i32 m0, s28, 0xe000
	s_nop 0
	global_load_lds_dwordx4 v[178:179], off
	s_waitcnt lgkmcnt(8)
	s_barrier
	s_waitcnt lgkmcnt(0)
	s_setprio 1
	s_waitcnt lgkmcnt(0)
	v_mfma_f32_16x16x32_bf16 v[126:129], v[130:133], v[146:149], 0
	v_mfma_f32_16x16x32_bf16 v[122:125], v[138:141], v[146:149], 0
	v_mfma_f32_16x16x32_bf16 v[110:113], v[130:133], v[154:157], 0
	v_mfma_f32_16x16x32_bf16 v[106:109], v[138:141], v[154:157], 0
	v_mfma_f32_16x16x32_bf16 v[92:95], v[130:133], v[162:165], 0
	v_mfma_f32_16x16x32_bf16 v[88:91], v[138:141], v[162:165], 0
	v_mfma_f32_16x16x32_bf16 v[76:79], v[130:133], v[170:173], 0
	v_mfma_f32_16x16x32_bf16 v[72:75], v[138:141], v[170:173], 0
	v_mfma_f32_16x16x32_bf16 v[126:129], v[134:137], v[150:153], v[126:129]
	v_mfma_f32_16x16x32_bf16 v[122:125], v[142:145], v[150:153], v[122:125]
	v_mfma_f32_16x16x32_bf16 v[110:113], v[134:137], v[158:161], v[110:113]
	v_mfma_f32_16x16x32_bf16 v[106:109], v[142:145], v[158:161], v[106:109]
	v_mfma_f32_16x16x32_bf16 v[92:95], v[134:137], v[166:169], v[92:95]
	v_mfma_f32_16x16x32_bf16 v[88:91], v[142:145], v[166:169], v[88:91]
	v_mfma_f32_16x16x32_bf16 v[76:79], v[134:137], v[174:177], v[76:79]
	v_mfma_f32_16x16x32_bf16 v[72:75], v[142:145], v[174:177], v[72:75]
	s_setprio 0
	s_barrier
	s_add_i32 s18, 0, 0x14000
	s_add_i32 s0, s0, s27
	v_add_u32_e32 v196, s18, v213
	v_lshl_add_u64 v[200:201], s[22:23], 0, v[96:97]
	s_mov_b32 m0, s0
	ds_read_b128 v[178:181], v196
	ds_read_b128 v[182:185], v196 offset:1024
	ds_read_b128 v[186:189], v196 offset:2048
	ds_read_b128 v[196:199], v196 offset:3072
	global_load_lds_dwordx4 v[200:201], off
	v_lshl_add_u64 v[202:203], s[22:23], 0, v[190:191]
	s_add_i32 m0, s0, 0x2000
	s_nop 0
	global_load_lds_dwordx4 v[202:203], off
	s_barrier
	s_waitcnt lgkmcnt(0)
	s_setprio 1
	s_waitcnt lgkmcnt(0)
	v_mfma_f32_16x16x32_bf16 v[118:121], v[178:181], v[146:149], 0
	v_mfma_f32_16x16x32_bf16 v[114:117], v[186:189], v[146:149], 0
	v_mfma_f32_16x16x32_bf16 v[102:105], v[178:181], v[154:157], 0
	v_mfma_f32_16x16x32_bf16 v[98:101], v[186:189], v[154:157], 0
	v_mfma_f32_16x16x32_bf16 v[84:87], v[178:181], v[162:165], 0
	v_mfma_f32_16x16x32_bf16 v[80:83], v[186:189], v[162:165], 0
	v_mfma_f32_16x16x32_bf16 v[68:71], v[178:181], v[170:173], 0
	v_mfma_f32_16x16x32_bf16 v[64:67], v[186:189], v[170:173], 0
	v_mfma_f32_16x16x32_bf16 v[118:121], v[182:185], v[150:153], v[118:121]
	v_mfma_f32_16x16x32_bf16 v[114:117], v[196:199], v[150:153], v[114:117]
	v_mfma_f32_16x16x32_bf16 v[102:105], v[182:185], v[158:161], v[102:105]
	v_mfma_f32_16x16x32_bf16 v[98:101], v[196:199], v[158:161], v[98:101]
	v_mfma_f32_16x16x32_bf16 v[84:87], v[182:185], v[166:169], v[84:87]
	v_mfma_f32_16x16x32_bf16 v[80:83], v[196:199], v[166:169], v[80:83]
	v_mfma_f32_16x16x32_bf16 v[68:71], v[182:185], v[174:177], v[68:71]
	v_mfma_f32_16x16x32_bf16 v[64:67], v[196:199], v[174:177], v[64:67]
	s_setprio 0
	s_mov_b32 m0, s28
	v_lshl_add_u64 v[204:205], s[24:25], 0, v[96:97]
	s_barrier
; #define PG8_STAGE(bufoff, gbase, voff) do { _Pragma("unroll") for (int _i = 0; _i < 2; ++_i) \
;         __builtin_amdgcn_global_load_lds((const unsigned*)((const char*)(gbase) + (voff)[_i]), (LAS unsigned*)(lds + (bufoff) + ldsw + _i * 8192), 16, 0, 0); } while (0)
; #define PG8_LDA(dst, b, h) do { _Pragma("unroll") for (int m = 0; m < 4; ++m) _Pragma("unroll") for (int k = 0; k < 2; ++k) dst[m][k] = *(const LAS bf16x8*)(lds + PG8_SA(b, h) + aoff + m * 2048 + k * 1024); } while (0)
; #define PG8_MMA(ai, bj, At, Bt) do { __builtin_amdgcn_s_setprio(1); _Pragma("unroll") for (int m = 0; m < 4; ++m) _Pragma("unroll") for (int n = 0; n < 2; ++n) _Pragma("unroll") for (int k = 0; k < 2; ++k) \
;         acc[ai][bj][m][n] = __builtin_amdgcn_mfma_f32_16x16x32_bf16(Bt[n][k], At[m][k], acc[ai][bj][m][n], 0, 0, 0); __builtin_amdgcn_s_setprio(0); } while (0)
; #define PG8_WAIT_V(n) asm volatile("s_waitcnt vmcnt(" #n ")" ::: "memory")
; #define PG8_WAIT_L(n) asm volatile("s_waitcnt lgkmcnt(" #n ")" ::: "memory")
; #define PG8_BAR __builtin_amdgcn_s_barrier()
; #define PG8_SCHED __builtin_amdgcn_sched_barrier(0)
; template <class Epi, class Sched>
; DI void gemm_phase(LAS unsigned char* lds, const Gemm g, const Sched& S, const Epi& E) {
;     ...
;             PG8_LDA(At, 0, 1); PG8_STAGE(PG8_SA(0, 0), a2, voffA);
;             PG8_BAR; PG8_WAIT_L(0); PG8_MMA(1, 0, At, B0); PG8_BAR; PG8_SCHED;
;             PG8_STAGE(PG8_SB(0, 1), b2 + hstep, voffB);
;             PG8_WAIT_V(6); PG8_BAR; PG8_MMA(1, 1, At, B1); PG8_BAR;
	ds_read_b128 v[146:149], v215 offset:16384
	ds_read_b128 v[150:153], v215 offset:17408
	ds_read_b128 v[154:157], v215 offset:18432
	ds_read_b128 v[158:161], v215 offset:19456
	ds_read_b128 v[162:165], v215 offset:20480
	ds_read_b128 v[166:169], v215 offset:21504
	ds_read_b128 v[170:173], v215 offset:22528
	ds_read_b128 v[174:177], v215 offset:23552
	global_load_lds_dwordx4 v[204:205], off
	v_lshl_add_u64 v[206:207], s[24:25], 0, v[190:191]
	s_mov_b32 m0, s29
	s_nop 0
	global_load_lds_dwordx4 v[206:207], off
	s_barrier
	s_waitcnt lgkmcnt(0)
	s_setprio 1
	s_waitcnt lgkmcnt(0)
	v_mfma_f32_16x16x32_bf16 v[60:63], v[130:133], v[146:149], 0
	v_mfma_f32_16x16x32_bf16 v[56:59], v[138:141], v[146:149], 0
	v_mfma_f32_16x16x32_bf16 v[44:47], v[130:133], v[154:157], 0
	v_mfma_f32_16x16x32_bf16 v[40:43], v[138:141], v[154:157], 0
	v_mfma_f32_16x16x32_bf16 v[28:31], v[130:133], v[162:165], 0
	v_mfma_f32_16x16x32_bf16 v[24:27], v[138:141], v[162:165], 0
	v_mfma_f32_16x16x32_bf16 v[12:15], v[130:133], v[170:173], 0
	v_mfma_f32_16x16x32_bf16 v[8:11], v[138:141], v[170:173], 0
	v_mfma_f32_16x16x32_bf16 v[60:63], v[134:137], v[150:153], v[60:63]
	v_mfma_f32_16x16x32_bf16 v[56:59], v[142:145], v[150:153], v[56:59]
	v_mfma_f32_16x16x32_bf16 v[44:47], v[134:137], v[158:161], v[44:47]
	v_mfma_f32_16x16x32_bf16 v[40:43], v[142:145], v[158:161], v[40:43]
	v_mfma_f32_16x16x32_bf16 v[28:31], v[134:137], v[166:169], v[28:31]
	v_mfma_f32_16x16x32_bf16 v[24:27], v[142:145], v[166:169], v[24:27]
	v_mfma_f32_16x16x32_bf16 v[12:15], v[134:137], v[174:177], v[12:15]
	v_mfma_f32_16x16x32_bf16 v[8:11], v[142:145], v[174:177], v[8:11]
	s_setprio 0
	s_barrier
	s_add_u32 s0, s22, 0xb0000
	s_addc_u32 s1, s23, 0
	s_add_i32 s18, s18, s27
	v_lshl_add_u64 v[130:131], s[0:1], 0, v[96:97]
	s_mov_b32 m0, s18
	s_nop 0
	global_load_lds_dwordx4 v[130:131], off
	v_lshl_add_u64 v[130:131], s[0:1], 0, v[190:191]
	s_add_i32 m0, s18, 0x2000
	s_nop 0
	global_load_lds_dwordx4 v[130:131], off
	s_waitcnt vmcnt(6)
	s_barrier
	s_setprio 1
	v_mfma_f32_16x16x32_bf16 v[52:55], v[178:181], v[146:149], 0
	v_mfma_f32_16x16x32_bf16 v[48:51], v[186:189], v[146:149], 0
	v_mfma_f32_16x16x32_bf16 v[36:39], v[178:181], v[154:157], 0
	v_mfma_f32_16x16x32_bf16 v[32:35], v[186:189], v[154:157], 0
	v_mfma_f32_16x16x32_bf16 v[20:23], v[178:181], v[162:165], 0
	v_mfma_f32_16x16x32_bf16 v[16:19], v[186:189], v[162:165], 0
	v_mfma_f32_16x16x32_bf16 v[4:7], v[178:181], v[170:173], 0
	v_mfma_f32_16x16x32_bf16 v[0:3], v[186:189], v[170:173], 0
	v_mfma_f32_16x16x32_bf16 v[52:55], v[182:185], v[150:153], v[52:55]
	v_mfma_f32_16x16x32_bf16 v[48:51], v[196:199], v[150:153], v[48:51]
	v_mfma_f32_16x16x32_bf16 v[36:39], v[182:185], v[158:161], v[36:39]
	v_mfma_f32_16x16x32_bf16 v[32:35], v[196:199], v[158:161], v[32:35]
	v_mfma_f32_16x16x32_bf16 v[20:23], v[182:185], v[166:169], v[20:23]
	v_mfma_f32_16x16x32_bf16 v[16:19], v[196:199], v[166:169], v[16:19]
	v_mfma_f32_16x16x32_bf16 v[4:7], v[182:185], v[174:177], v[4:7]
	v_mfma_f32_16x16x32_bf16 v[0:3], v[196:199], v[174:177], v[0:3]
	s_setprio 0
	s_branch .Lkmid_28804

; #define PG8_STAGE(bufoff, gbase, voff) do { _Pragma("unroll") for (int _i = 0; _i < 2; ++_i) \
;         __builtin_amdgcn_global_load_lds((const unsigned*)((const char*)(gbase) + (voff)[_i]), (LAS unsigned*)(lds + (bufoff) + ldsw + _i * 8192), 16, 0, 0); } while (0)
; #define PG8_LDA(dst, b, h) do { _Pragma("unroll") for (int m = 0; m < 4; ++m) _Pragma("unroll") for (int k = 0; k < 2; ++k) dst[m][k] = *(const LAS bf16x8*)(lds + PG8_SA(b, h) + aoff + m * 2048 + k * 1024); } while (0)
; #define PG8_LDB(dst, b, h) do { _Pragma("unroll") for (int n = 0; n < 2; ++n) _Pragma("unroll") for (int k = 0; k < 2; ++k) dst[n][k] = *(const LAS bf16x8*)(lds + PG8_SB(b, h) + boff + n * 2048 + k * 1024); } while (0)
; #define PG8_MMA(ai, bj, At, Bt) do { __builtin_amdgcn_s_setprio(1); _Pragma("unroll") for (int m = 0; m < 4; ++m) _Pragma("unroll") for (int n = 0; n < 2; ++n) _Pragma("unroll") for (int k = 0; k < 2; ++k) \
;         acc[ai][bj][m][n] = __builtin_amdgcn_mfma_f32_16x16x32_bf16(Bt[n][k], At[m][k], acc[ai][bj][m][n], 0, 0, 0); __builtin_amdgcn_s_setprio(0); } while (0)
; #define PG8_WAIT_L(n) asm volatile("s_waitcnt lgkmcnt(" #n ")" ::: "memory")
; #define PG8_BAR __builtin_amdgcn_s_barrier()
; #define PG8_SCHED __builtin_amdgcn_sched_barrier(0)
; template <class Epi, class Sched>
; DI void gemm_phase(LAS unsigned char* lds, const Gemm g, const Sched& S, const Epi& E) {
;     ...
;             PG8_LDB(B0, 1, 0); PG8_SCHED; PG8_LDA(At, 1, 0); PG8_STAGE(PG8_SA(0, 1), a2 + hstep, voffA);
;             PG8_WAIT_L(8); PG8_BAR; PG8_WAIT_L(0); PG8_MMA(0, 0, At, B0); PG8_BAR; PG8_SCHED;
;             PG8_LDB(B1, 1, 1); PG8_STAGE(PG8_SB(1, 0), b3, voffB);
;             PG8_BAR; PG8_WAIT_L(0); PG8_MMA(0, 1, At, B1); PG8_BAR;
;             PG8_LDA(At, 1, 1); PG8_STAGE(PG8_SA(1, 0), a3, voffA);
;             PG8_BAR; PG8_WAIT_L(0); PG8_MMA(1, 0, At, B0); PG8_BAR; PG8_SCHED;
.Lkmid_28804:
	s_add_i32 s18, 0, 0x18000
	v_add_u32_e32 v142, s18, v213
	s_barrier
	ds_read_b128 v[130:133], v142
	ds_read_b128 v[134:137], v142 offset:1024
	ds_read_b128 v[138:141], v142 offset:2048
	ds_read_b128 v[142:145], v142 offset:3072
	s_add_u32 s0, s24, 0xb0000
	s_addc_u32 s1, s25, 0
	s_mov_b32 m0, s30
	v_lshl_add_u64 v[178:179], s[0:1], 0, v[96:97]
	ds_read_b128 v[146:149], v215 offset:32768
	ds_read_b128 v[150:153], v215 offset:33792
	ds_read_b128 v[154:157], v215 offset:34816
	ds_read_b128 v[158:161], v215 offset:35840
	ds_read_b128 v[162:165], v215 offset:36864
	ds_read_b128 v[166:169], v215 offset:37888
	ds_read_b128 v[170:173], v215 offset:38912
	ds_read_b128 v[174:177], v215 offset:39936
	global_load_lds_dwordx4 v[178:179], off
	v_lshl_add_u64 v[178:179], s[0:1], 0, v[190:191]
	s_mov_b32 m0, s31
	s_nop 0
	global_load_lds_dwordx4 v[178:179], off
	s_waitcnt lgkmcnt(8)
	s_barrier
	s_waitcnt lgkmcnt(0)
	s_setprio 1
	s_waitcnt lgkmcnt(0)
	v_mfma_f32_16x16x32_bf16 v[126:129], v[130:133], v[146:149], v[126:129]
	v_mfma_f32_16x16x32_bf16 v[122:125], v[138:141], v[146:149], v[122:125]
	v_mfma_f32_16x16x32_bf16 v[110:113], v[130:133], v[154:157], v[110:113]
	v_mfma_f32_16x16x32_bf16 v[106:109], v[138:141], v[154:157], v[106:109]
	v_mfma_f32_16x16x32_bf16 v[92:95], v[130:133], v[162:165], v[92:95]
	v_mfma_f32_16x16x32_bf16 v[88:91], v[138:141], v[162:165], v[88:91]
	v_mfma_f32_16x16x32_bf16 v[76:79], v[130:133], v[170:173], v[76:79]
	v_mfma_f32_16x16x32_bf16 v[72:75], v[138:141], v[170:173], v[72:75]
	v_mfma_f32_16x16x32_bf16 v[126:129], v[134:137], v[150:153], v[126:129]
	v_mfma_f32_16x16x32_bf16 v[122:125], v[142:145], v[150:153], v[122:125]
	v_mfma_f32_16x16x32_bf16 v[110:113], v[134:137], v[158:161], v[110:113]
	v_mfma_f32_16x16x32_bf16 v[106:109], v[142:145], v[158:161], v[106:109]
	v_mfma_f32_16x16x32_bf16 v[92:95], v[134:137], v[166:169], v[92:95]
	v_mfma_f32_16x16x32_bf16 v[88:91], v[142:145], v[166:169], v[88:91]
	v_mfma_f32_16x16x32_bf16 v[76:79], v[134:137], v[174:177], v[76:79]
	v_mfma_f32_16x16x32_bf16 v[72:75], v[142:145], v[174:177], v[72:75]
	s_setprio 0
	s_barrier
	s_add_i32 s19, 0, 0x1c000
	s_add_i32 s0, s18, s27
	v_add_u32_e32 v196, s19, v213
	v_lshl_add_u64 v[200:201], v[200:201], 0, s[36:37]
	s_mov_b32 m0, s0
	ds_read_b128 v[178:181], v196
	ds_read_b128 v[182:185], v196 offset:1024
	ds_read_b128 v[186:189], v196 offset:2048
	ds_read_b128 v[196:199], v196 offset:3072
	global_load_lds_dwordx4 v[200:201], off
	v_lshl_add_u64 v[200:201], v[202:203], 0, s[36:37]
	s_add_i32 m0, s0, 0x2000
	s_nop 0
	global_load_lds_dwordx4 v[200:201], off
	s_barrier
	s_waitcnt lgkmcnt(0)
	s_setprio 1
	s_waitcnt lgkmcnt(0)
	v_mfma_f32_16x16x32_bf16 v[118:121], v[178:181], v[146:149], v[118:121]
	v_mfma_f32_16x16x32_bf16 v[114:117], v[186:189], v[146:149], v[114:117]
	v_mfma_f32_16x16x32_bf16 v[102:105], v[178:181], v[154:157], v[102:105]
	v_mfma_f32_16x16x32_bf16 v[98:101], v[186:189], v[154:157], v[98:101]
	v_mfma_f32_16x16x32_bf16 v[84:87], v[178:181], v[162:165], v[84:87]
	v_mfma_f32_16x16x32_bf16 v[80:83], v[186:189], v[162:165], v[80:83]
	v_mfma_f32_16x16x32_bf16 v[68:71], v[178:181], v[170:173], v[68:71]
	v_mfma_f32_16x16x32_bf16 v[64:67], v[186:189], v[170:173], v[64:67]
	v_mfma_f32_16x16x32_bf16 v[118:121], v[182:185], v[150:153], v[118:121]
	v_mfma_f32_16x16x32_bf16 v[114:117], v[196:199], v[150:153], v[114:117]
	v_mfma_f32_16x16x32_bf16 v[102:105], v[182:185], v[158:161], v[102:105]
	v_mfma_f32_16x16x32_bf16 v[98:101], v[196:199], v[158:161], v[98:101]
	v_mfma_f32_16x16x32_bf16 v[84:87], v[182:185], v[166:169], v[84:87]
	v_mfma_f32_16x16x32_bf16 v[80:83], v[196:199], v[166:169], v[80:83]
	v_mfma_f32_16x16x32_bf16 v[68:71], v[182:185], v[174:177], v[68:71]
	v_mfma_f32_16x16x32_bf16 v[64:67], v[196:199], v[174:177], v[64:67]
	s_setprio 0
	s_mov_b32 m0, s45
	v_lshl_add_u64 v[200:201], v[204:205], 0, s[36:37]
	s_barrier
	ds_read_b128 v[146:149], v215 offset:49152
	ds_read_b128 v[150:153], v215 offset:50176
	ds_read_b128 v[154:157], v215 offset:51200
	ds_read_b128 v[158:161], v215 offset:52224
	ds_read_b128 v[162:165], v215 offset:53248
	ds_read_b128 v[166:169], v215 offset:54272
	ds_read_b128 v[170:173], v215 offset:55296
	ds_read_b128 v[174:177], v215 offset:56320
	global_load_lds_dwordx4 v[200:201], off
	v_lshl_add_u64 v[200:201], v[206:207], 0, s[36:37]
	s_mov_b32 m0, s46
	s_nop 0
	global_load_lds_dwordx4 v[200:201], off
	s_barrier
	s_waitcnt lgkmcnt(0)
	s_setprio 1
	s_waitcnt lgkmcnt(0)
	v_mfma_f32_16x16x32_bf16 v[60:63], v[130:133], v[146:149], v[60:63]
	v_mfma_f32_16x16x32_bf16 v[56:59], v[138:141], v[146:149], v[56:59]
	v_mfma_f32_16x16x32_bf16 v[44:47], v[130:133], v[154:157], v[44:47]
	v_mfma_f32_16x16x32_bf16 v[40:43], v[138:141], v[154:157], v[40:43]
	v_mfma_f32_16x16x32_bf16 v[28:31], v[130:133], v[162:165], v[28:31]
	v_mfma_f32_16x16x32_bf16 v[24:27], v[138:141], v[162:165], v[24:27]
	v_mfma_f32_16x16x32_bf16 v[12:15], v[130:133], v[170:173], v[12:15]
	v_mfma_f32_16x16x32_bf16 v[8:11], v[138:141], v[170:173], v[8:11]
	v_mfma_f32_16x16x32_bf16 v[60:63], v[134:137], v[150:153], v[60:63]
	v_mfma_f32_16x16x32_bf16 v[56:59], v[142:145], v[150:153], v[56:59]
	v_mfma_f32_16x16x32_bf16 v[44:47], v[134:137], v[158:161], v[44:47]
	v_mfma_f32_16x16x32_bf16 v[40:43], v[142:145], v[158:161], v[40:43]
	v_mfma_f32_16x16x32_bf16 v[28:31], v[134:137], v[166:169], v[28:31]
	v_mfma_f32_16x16x32_bf16 v[24:27], v[142:145], v[166:169], v[24:27]
	v_mfma_f32_16x16x32_bf16 v[12:15], v[134:137], v[174:177], v[12:15]
	v_mfma_f32_16x16x32_bf16 v[8:11], v[142:145], v[174:177], v[8:11]
	s_setprio 0
	s_barrier
; #define LAS __attribute__((address_space(3)))
; DI unsigned pk2(float lo, float hi) { f32x2 v = {lo, hi}; hbf2 r = __builtin_convertvector(v, hbf2); return __builtin_bit_cast(unsigned, r); }
; #define PG8_STAGE(bufoff, gbase, voff) do { _Pragma("unroll") for (int _i = 0; _i < 2; ++_i) \
;         __builtin_amdgcn_global_load_lds((const unsigned*)((const char*)(gbase) + (voff)[_i]), (LAS unsigned*)(lds + (bufoff) + ldsw + _i * 8192), 16, 0, 0); } while (0)
; #define PG8_WAIT_V(n) asm volatile("s_waitcnt vmcnt(" #n ")" ::: "memory")
; #define PG8_BAR __builtin_amdgcn_s_barrier()
; template <class Epi, class Sched>
; DI void gemm_phase(LAS unsigned char* lds, const Gemm g, const Sched& S, const Epi& E) {
;     ...
;             PG8_STAGE(PG8_SB(1, 1), b3 + hstep, voffB);
;             PG8_WAIT_V(6); PG8_BAR; PG8_MMA(1, 1, At, B1); PG8_BAR;
;     DI void operator()(f32x4 (&acc)[2][2][4][2], const Unit& u, int wr, int wc, int fr, int fq, LAS unsigned char* lds) const {
;         const int row0 = u.pm * 256 + wr * 64 + fr, col0 = u.pn * 256 + wc * 32 + 4 * fq;
; #pragma unroll
;         for (int ai = 0; ai < 2; ++ai) {
;             f32x4 xv[4][2][2];
; #pragma unroll
;             for (int m = 0; m < 4; ++m) {
;                 const int row = row0 + ai * 128 + m * 16;
;                 const float* xi = (row < TP ? xin_p + (size_t)row * DM : xin_s + (size_t)(row - TP) * DM) + col0;
; #pragma unroll
;                 for (int bj = 0; bj < 2; ++bj)
; #pragma unroll
;                     for (int n = 0; n < 2; ++n) xv[m][bj][n] = *(const f32x4*)(xi + bj * 128 + n * 16);
;             }
; #pragma unroll
;             for (int m = 0; m < 4; ++m) {
;                 const int row = row0 + ai * 128 + m * 16;
;                 float* xo = X + (size_t)row * DM + col0; bf16_t* xb = XB + (size_t)row * DM + col0;
;                 float ssq = 0.f;
; #pragma unroll
;                 for (int bj = 0; bj < 2; ++bj)
; #pragma unroll
;                     for (int n = 0; n < 2; ++n) {
;                         const int c = bj * 128 + n * 16;
;                         const f32x4 o = xv[m][bj][n] + acc[ai][bj][m][n] * scale;
;                         *(f32x4*)(xo + c) = o;
;                         if (wxb) { u32x2 w; w.x = pk2(o[0], o[1]); w.y = pk2(o[2], o[3]); *(u32x2*)(xb + c) = w; }
	s_add_u32 s0, s22, 0xb0080
	s_addc_u32 s1, s23, 0
	s_add_i32 s18, s19, s27
	v_lshl_add_u64 v[130:131], s[0:1], 0, v[96:97]
	s_mov_b32 m0, s18
	s_nop 0
	global_load_lds_dwordx4 v[130:131], off
	v_lshl_add_u64 v[130:131], s[0:1], 0, v[190:191]
	s_add_i32 m0, s18, 0x2000
	s_nop 0
	global_load_lds_dwordx4 v[130:131], off
	s_waitcnt vmcnt(6)
	s_barrier
	s_setprio 1
	v_mfma_f32_16x16x32_bf16 v[52:55], v[178:181], v[146:149], v[52:55]
	v_mfma_f32_16x16x32_bf16 v[48:51], v[186:189], v[146:149], v[48:51]
	v_mfma_f32_16x16x32_bf16 v[36:39], v[178:181], v[154:157], v[36:39]
	v_mfma_f32_16x16x32_bf16 v[32:35], v[186:189], v[154:157], v[32:35]
	v_mfma_f32_16x16x32_bf16 v[20:23], v[178:181], v[162:165], v[20:23]
	v_mfma_f32_16x16x32_bf16 v[16:19], v[186:189], v[162:165], v[16:19]
	v_mfma_f32_16x16x32_bf16 v[4:7], v[178:181], v[170:173], v[4:7]
	v_mfma_f32_16x16x32_bf16 v[0:3], v[186:189], v[170:173], v[0:3]
	v_mfma_f32_16x16x32_bf16 v[52:55], v[182:185], v[150:153], v[52:55]
	v_mfma_f32_16x16x32_bf16 v[48:51], v[196:199], v[150:153], v[48:51]
	v_mfma_f32_16x16x32_bf16 v[36:39], v[182:185], v[158:161], v[36:39]
	v_mfma_f32_16x16x32_bf16 v[32:35], v[196:199], v[158:161], v[32:35]
	v_mfma_f32_16x16x32_bf16 v[20:23], v[182:185], v[166:169], v[20:23]
	v_mfma_f32_16x16x32_bf16 v[16:19], v[196:199], v[166:169], v[16:19]
	v_mfma_f32_16x16x32_bf16 v[4:7], v[182:185], v[174:177], v[4:7]
	v_mfma_f32_16x16x32_bf16 v[0:3], v[196:199], v[174:177], v[0:3]
	s_setprio 0
	s_add_i32 s39, s39, 2
	s_add_u32 s34, s34, 0x100
	s_addc_u32 s38, s38, 0
	s_cmp_lt_u32 s39, 42
	s_mov_b64 s[18:19], s[20:21]
	s_barrier
	s_cbranch_scc1 .LBB0_1957
	v_lshl_add_u32 v198, s2, 8, v212
	v_add_u32_e32 v130, 0xffff8000, v198
	v_ashrrev_i32_e32 v199, 31, v198
	v_cmp_gt_i32_e32 vcc, s86, v198
	v_lshl_or_b32 v196, s51, 8, v214
	v_mov_b32_e32 v134, s7
	v_cndmask_b32_e32 v131, 0, v199, vcc
	v_cndmask_b32_e32 v130, v130, v198, vcc
	v_mov_b32_e32 v135, s42
	v_mov_b32_e32 v136, s6
	v_mov_b32_e32 v137, s43
	v_ashrrev_i32_e32 v197, 31, v196
	v_cndmask_b32_e32 v133, v134, v135, vcc
	v_cndmask_b32_e32 v132, v136, v137, vcc
	v_lshlrev_b64 v[130:131], 12, v[130:131]
	v_lshl_add_u64 v[130:131], v[132:133], 0, v[130:131]
	v_lshlrev_b64 v[200:201], 2, v[196:197]
	v_lshl_add_u64 v[130:131], v[130:131], 0, v[200:201]
	v_or_b32_e32 v206, 16, v198
	global_load_dwordx4 v[216:219], v[130:131], off
	global_load_dwordx4 v[186:189], v[130:131], off offset:64
	global_load_dwordx4 v[182:185], v[130:131], off offset:512
	global_load_dwordx4 v[178:181], v[130:131], off offset:576
	v_ashrrev_i32_e32 v207, 31, v206
	v_add_u32_e32 v130, 0xffff8010, v198
	v_cmp_gt_i32_e32 vcc, s86, v206
	v_or_b32_e32 v204, 32, v198
	v_ashrrev_i32_e32 v205, 31, v204
	v_cndmask_b32_e32 v131, 0, v207, vcc
	v_cndmask_b32_e32 v130, v130, v206, vcc
	v_cndmask_b32_e32 v133, v134, v135, vcc
	v_cndmask_b32_e32 v132, v136, v137, vcc
	v_lshlrev_b64 v[130:131], 12, v[130:131]
	v_lshl_add_u64 v[130:131], v[132:133], 0, v[130:131]
	v_lshl_add_u64 v[130:131], v[130:131], 0, v[200:201]
	global_load_dwordx4 v[174:177], v[130:131], off
	global_load_dwordx4 v[170:173], v[130:131], off offset:64
	global_load_dwordx4 v[166:169], v[130:131], off offset:512
	global_load_dwordx4 v[162:165], v[130:131], off offset:576
	v_add_u32_e32 v130, 0xffff8020, v198
	v_cmp_gt_i32_e32 vcc, s86, v204
	v_or_b32_e32 v202, 48, v198
	v_ashrrev_i32_e32 v203, 31, v202
	v_cndmask_b32_e32 v131, 0, v205, vcc
	v_cndmask_b32_e32 v130, v130, v204, vcc
	v_cndmask_b32_e32 v133, v134, v135, vcc
	v_cndmask_b32_e32 v132, v136, v137, vcc
	v_lshlrev_b64 v[130:131], 12, v[130:131]
	v_lshl_add_u64 v[130:131], v[132:133], 0, v[130:131]
	v_lshl_add_u64 v[130:131], v[130:131], 0, v[200:201]
	global_load_dwordx4 v[158:161], v[130:131], off
	global_load_dwordx4 v[154:157], v[130:131], off offset:64
	global_load_dwordx4 v[150:153], v[130:131], off offset:512
	global_load_dwordx4 v[146:149], v[130:131], off offset:576
	v_add_u32_e32 v130, 0xffff8030, v198
	v_cmp_gt_i32_e32 vcc, s86, v202
	v_cndmask_b32_e64 v208, 0, 1, s[10:11]
	v_cmp_ne_u32_e64 s[38:39], 1, v208
	v_cndmask_b32_e32 v131, 0, v203, vcc
	v_cndmask_b32_e32 v130, v130, v202, vcc
	v_cndmask_b32_e32 v133, v134, v135, vcc
	v_cndmask_b32_e32 v132, v136, v137, vcc
	v_lshlrev_b64 v[130:131], 12, v[130:131]
	v_lshl_add_u64 v[130:131], v[132:133], 0, v[130:131]
	v_lshl_add_u64 v[130:131], v[130:131], 0, v[200:201]
	global_load_dwordx4 v[142:145], v[130:131], off
	global_load_dwordx4 v[138:141], v[130:131], off offset:64
	global_load_dwordx4 v[134:137], v[130:131], off offset:512
	s_nop 0
	global_load_dwordx4 v[130:133], v[130:131], off offset:576
	v_lshlrev_b64 v[208:209], 12, v[198:199]
	v_lshlrev_b64 v[210:211], 11, v[198:199]
	v_lshl_add_u64 v[208:209], s[90:91], 0, v[208:209]
	v_lshl_add_u64 v[220:221], s[72:73], 0, v[210:211]
	v_lshl_add_u64 v[210:211], v[208:209], 0, v[200:201]
	v_lshl_add_u64 v[208:209], v[196:197], 1, v[220:221]
	s_andn2_b64 vcc, exec, s[10:11]
	s_waitcnt vmcnt(0)
	v_pk_fma_f32 v[128:129], v[128:129], 0.5, v[218:219] op_sel_hi:[1,0,1]
	v_pk_fma_f32 v[126:127], v[126:127], 0.5, v[216:217] op_sel_hi:[1,0,1]
	global_store_dwordx4 v[210:211], v[126:129], off
	s_cbranch_vccnz .LBB0_1960
	v_cvt_pk_bf16_f32 v216, v126, v127
	v_cvt_pk_bf16_f32 v217, v128, v129
	global_store_dwordx2 v[208:209], v[216:217], off
